# attention: row-sum exchanges ride on the PV phase's LDS waits, branch-0 V^T fragments double-buffered in the idle Q registers
# speedup vs baseline: 1.0274x; 1.0140x over previous
.Latt_unit:
	s_mov_b32 s33, s12
	s_mov_b32 s34, s15
	s_mov_b32 s35, s16
	s_mov_b32 s36, s17
	s_mov_b32 s38, s14
	s_mov_b32 s39, s13
	s_mov_b32 s24, s20
	s_mov_b32 s25, s21
	s_mov_b32 s26, s22
	s_mov_b32 s27, s23
	s_mov_b32 s40, s42
	s_mov_b32 s41, s43
	v_mov_b32_e32 v173, v176
	v_mov_b32_e32 v174, v177
	s_lshr_b32 s44, s33, 0
	s_lshr_b32 s2, s0, 2
	s_lshl_b32 s2, s2, 5
	s_lshr_b32 s3, s15, 2
	s_add_i32 s42, s3, s2
	s_and_b32 s43, s0, 3
	s_waitcnt vmcnt(4)
	ds_write_b128 v253, v[0:3]
	ds_write_b128 v253, v[4:7] offset:1152
	ds_write_b128 v253, v[8:11] offset:2304
	ds_write_b128 v253, v[12:15] offset:3456
	ds_write_b128 v253, v[16:19] offset:4608
	ds_write_b128 v253, v[20:23] offset:5760
	ds_write_b128 v253, v[24:27] offset:55296
	ds_write_b128 v253, v[28:31] offset:56448
	ds_write_b128 v253, v[32:35] offset:57600
	ds_write_b128 v253, v[36:39] offset:58752
	ds_write_b128 v253, v[40:43] offset:59904
	ds_write_b128 v253, v[44:47] offset:61056
	s_lshl_b32 s2, s0, 12
	s_add_i32 s2, s2, 0x1b500
	v_and_b32_e32 v141, 63, v145
	v_lshl_add_u32 v141, v141, 4, s2
	ds_write_b128 v141, v[48:51]
	ds_write_b128 v141, v[52:55] offset:1024
	ds_write_b128 v141, v[56:59] offset:2048
	ds_write_b128 v141, v[60:63] offset:3072
	s_waitcnt lgkmcnt(0)
	s_barrier
	v_add_u32_e32 v134, s42, v160
	v_lshlrev_b32_e32 v134, 2, v134
	v_add_u32_e32 v134, s43, v134
	v_subrev_u32_e32 v135, s15, v134
	v_lshrrev_b32_e32 v136, 4, v135
	v_add_u32_e32 v136, v136, v135
	v_mad_u32_u24 v176, v136, s79, v161
	v_lshl_add_u32 v177, v135, 2, s80
	s_lshl_b32 s2, s43, s13
	s_lshl_b32 s2, s2, 7
	s_add_u32 s86, s20, s2
	s_addc_u32 s87, s21, 0
	s_add_i32 s2, s42, -64
	v_add_u32_e32 v136, s2, v164
	v_ashrrev_i32_e32 v136, 2, v136
	v_med3_i32 v136, v136, 0, s14
	v_lshl_add_u32 v136, v136, 9, v178
	global_load_dwordx4 v[0:3], v136, s[86:87]
	s_add_i32 s2, s42, -56
	v_add_u32_e32 v135, s2, v164
	v_ashrrev_i32_e32 v135, 2, v135
	v_med3_i32 v135, v135, 0, s14
	v_lshl_add_u32 v135, v135, 9, v178
	global_load_dwordx4 v[4:7], v135, s[86:87]
	s_add_i32 s2, s42, -48
	v_add_u32_e32 v136, s2, v164
	v_ashrrev_i32_e32 v136, 2, v136
	v_med3_i32 v136, v136, 0, s14
	v_lshl_add_u32 v136, v136, 9, v178
	global_load_dwordx4 v[8:11], v136, s[86:87]
	s_add_i32 s2, s42, -40
	v_add_u32_e32 v135, s2, v164
	v_ashrrev_i32_e32 v135, 2, v135
	v_med3_i32 v135, v135, 0, s14
	v_lshl_add_u32 v135, v135, 9, v178
	global_load_dwordx4 v[12:15], v135, s[86:87]
	s_add_i32 s2, s42, -32
	v_add_u32_e32 v136, s2, v164
	v_ashrrev_i32_e32 v136, 2, v136
	v_med3_i32 v136, v136, 0, s14
	v_lshl_add_u32 v136, v136, 9, v178
	global_load_dwordx4 v[16:19], v136, s[86:87]
	s_add_i32 s2, s42, -24
	v_add_u32_e32 v135, s2, v164
	v_ashrrev_i32_e32 v135, 2, v135
	v_med3_i32 v135, v135, 0, s14
	v_lshl_add_u32 v135, v135, 9, v178
	global_load_dwordx4 v[20:23], v135, s[86:87]
	s_add_i32 s2, s42, -16
	v_add_u32_e32 v136, s2, v164
	v_ashrrev_i32_e32 v136, 2, v136
	v_med3_i32 v136, v136, 0, s14
	v_lshl_add_u32 v136, v136, 9, v178
	global_load_dwordx4 v[24:27], v136, s[86:87]
	s_add_i32 s2, s42, -8
	v_add_u32_e32 v135, s2, v164
	v_ashrrev_i32_e32 v135, 2, v135
	v_med3_i32 v135, v135, 0, s14
	v_lshl_add_u32 v135, v135, 9, v178
	global_load_dwordx4 v[28:31], v135, s[86:87]
	s_add_i32 s2, s42, 0
	v_add_u32_e32 v136, s2, v164
	v_ashrrev_i32_e32 v136, 2, v136
	v_med3_i32 v136, v136, 0, s14
	v_lshl_add_u32 v136, v136, 9, v178
	global_load_dwordx4 v[32:35], v136, s[86:87]
	s_add_i32 s2, s42, 8
	v_add_u32_e32 v135, s2, v164
	v_ashrrev_i32_e32 v135, 2, v135
	v_med3_i32 v135, v135, 0, s14
	v_lshl_add_u32 v135, v135, 9, v178
	global_load_dwordx4 v[36:39], v135, s[86:87]
	s_add_i32 s2, s42, 16
	v_add_u32_e32 v136, s2, v164
	v_ashrrev_i32_e32 v136, 2, v136
	v_med3_i32 v136, v136, 0, s14
	v_lshl_add_u32 v136, v136, 9, v178
	global_load_dwordx4 v[40:43], v136, s[86:87]
	s_add_i32 s2, s42, 24
	v_add_u32_e32 v135, s2, v164
	v_ashrrev_i32_e32 v135, 2, v135
	v_med3_i32 v135, v135, 0, s14
	v_lshl_add_u32 v135, v135, 9, v178
	global_load_dwordx4 v[44:47], v135, s[86:87]
	s_lshl_b32 s2, s43, s13
	s_lshl_b32 s2, s2, 7
	s_add_u32 s74, s22, s2
	s_addc_u32 s75, s23, 0
	s_add_i32 s2, s42, -64
	v_add_u32_e32 v137, s2, v164
	v_ashrrev_i32_e32 v137, 2, v137
	v_med3_i32 v137, v137, 0, s14
	v_lshl_add_u32 v137, v137, 9, v178
	global_load_dwordx4 v[64:67], v137, s[74:75]
	s_add_i32 s2, s42, -56
	v_add_u32_e32 v137, s2, v164
	v_ashrrev_i32_e32 v137, 2, v137
	v_med3_i32 v137, v137, 0, s14
	v_lshl_add_u32 v137, v137, 9, v178
	global_load_dwordx4 v[68:71], v137, s[74:75]
	s_add_i32 s2, s42, -48
	v_add_u32_e32 v137, s2, v164
	v_ashrrev_i32_e32 v137, 2, v137
	v_med3_i32 v137, v137, 0, s14
	v_lshl_add_u32 v137, v137, 9, v178
	global_load_dwordx4 v[72:75], v137, s[74:75]
	s_add_i32 s2, s42, -40
	v_add_u32_e32 v137, s2, v164
	v_ashrrev_i32_e32 v137, 2, v137
	v_med3_i32 v137, v137, 0, s14
	v_lshl_add_u32 v137, v137, 9, v178
	global_load_dwordx4 v[76:79], v137, s[74:75]
	s_lshl_b32 s2, s43, s13
	s_lshl_b32 s2, s2, 7
	s_add_u32 s74, s22, s2
	s_addc_u32 s75, s23, 0
	s_add_i32 s2, s42, -32
	v_add_u32_e32 v137, s2, v164
	v_ashrrev_i32_e32 v137, 2, v137
	v_med3_i32 v137, v137, 0, s14
	v_lshl_add_u32 v137, v137, 9, v178
	global_load_dwordx4 v[80:83], v137, s[74:75]
	s_add_i32 s2, s42, -24
	v_add_u32_e32 v137, s2, v164
	v_ashrrev_i32_e32 v137, 2, v137
	v_med3_i32 v137, v137, 0, s14
	v_lshl_add_u32 v137, v137, 9, v178
	global_load_dwordx4 v[84:87], v137, s[74:75]
	s_add_i32 s2, s42, -16
	v_add_u32_e32 v137, s2, v164
	v_ashrrev_i32_e32 v137, 2, v137
	v_med3_i32 v137, v137, 0, s14
	v_lshl_add_u32 v137, v137, 9, v178
	global_load_dwordx4 v[88:91], v137, s[74:75]
	s_add_i32 s2, s42, -8
	v_add_u32_e32 v137, s2, v164
	v_ashrrev_i32_e32 v137, 2, v137
	v_med3_i32 v137, v137, 0, s14
	v_lshl_add_u32 v137, v137, 9, v178
	global_load_dwordx4 v[92:95], v137, s[74:75]
	s_lshl_b32 s2, s43, s13
	s_lshl_b32 s2, s2, 7
	s_add_u32 s74, s22, s2
	s_addc_u32 s75, s23, 0
	s_add_i32 s2, s42, 0
	v_add_u32_e32 v137, s2, v164
	v_ashrrev_i32_e32 v137, 2, v137
	v_med3_i32 v137, v137, 0, s14
	v_lshl_add_u32 v137, v137, 9, v178
	global_load_dwordx4 v[96:99], v137, s[74:75]
	s_add_i32 s2, s42, 8
	v_add_u32_e32 v137, s2, v164
	v_ashrrev_i32_e32 v137, 2, v137
	v_med3_i32 v137, v137, 0, s14
	v_lshl_add_u32 v137, v137, 9, v178
	global_load_dwordx4 v[100:103], v137, s[74:75]
	s_add_i32 s2, s42, 16
	v_add_u32_e32 v137, s2, v164
	v_ashrrev_i32_e32 v137, 2, v137
	v_med3_i32 v137, v137, 0, s14
	v_lshl_add_u32 v137, v137, 9, v178
	global_load_dwordx4 v[104:107], v137, s[74:75]
	s_add_i32 s2, s42, 24
	v_add_u32_e32 v137, s2, v164
	v_ashrrev_i32_e32 v137, 2, v137
	v_med3_i32 v137, v137, 0, s14
	v_lshl_add_u32 v137, v137, 9, v178
	global_load_dwordx4 v[108:111], v137, s[74:75]
	v_subrev_u32_e32 v143, s80, v174
	v_lshl_add_u32 v143, v143, 5, v161
	v_add_u32_e32 v143, 0x1b500, v143
	ds_read_b128 v[48:51], v143
	ds_read_b128 v[52:55], v143 offset:64
	ds_read_b128 v[56:59], v143 offset:2048
	ds_read_b128 v[60:63], v143 offset:2112
	s_waitcnt lgkmcnt(0)
	v_mov_b32_e32 v138, 0
	v_mov_b32_e32 v139, 0
	v_mov_b32_e32 v140, 0
	v_mov_b32_e32 v141, 0
	ds_read_b128 v[204:207], v149
	ds_read_b128 v[208:211], v149 offset:64
	ds_read_b128 v[212:215], v149 offset:2304
	ds_read_b128 v[216:219], v149 offset:2368
	ds_read_b128 v[220:223], v149 offset:4608
	ds_read_b128 v[224:227], v149 offset:4672
	ds_read_b128 v[228:231], v149 offset:6912
	ds_read_b128 v[232:235], v149 offset:6976
	s_waitcnt lgkmcnt(0)
	v_mfma_f32_16x16x32_bf16 v[236:239], v[204:207], v[48:51], 0
	v_mfma_f32_16x16x32_bf16 v[236:239], v[208:211], v[52:55], v[236:239]
	v_mfma_f32_16x16x32_bf16 v[240:243], v[212:215], v[48:51], 0
	v_mfma_f32_16x16x32_bf16 v[240:243], v[216:219], v[52:55], v[240:243]
	v_mfma_f32_16x16x32_bf16 v[248:251], v[212:215], v[56:59], 0
	v_mfma_f32_16x16x32_bf16 v[248:251], v[216:219], v[60:63], v[248:251]
	s_nop 7
	s_add_i32 s77, s40, -64
	s_cmp_lt_u32 s77, s44
	s_cselect_b32 s76, s70, s71
	v_min_f32_e32 v152, s76, v236
	v_min_f32_e32 v153, s76, v237
	v_min_f32_e32 v154, s76, v238
	v_min_f32_e32 v155, s76, v239
	v_mfma_f32_16x16x32_bf16 v[236:239], v[220:223], v[48:51], 0
	v_mfma_f32_16x16x32_bf16 v[236:239], v[224:227], v[52:55], v[236:239]
	v_mfma_f32_16x16x32_bf16 v[244:247], v[220:223], v[56:59], 0
	v_mfma_f32_16x16x32_bf16 v[244:247], v[224:227], v[60:63], v[244:247]
	ds_read_b128 v[204:207], v149 offset:9216
	ds_read_b128 v[208:211], v149 offset:9280
	v_pk_mul_f32 v[152:153], v[152:153], s[72:73]
	v_pk_mul_f32 v[154:155], v[154:155], s[72:73]
	v_exp_f32_e32 v152, v152
	v_exp_f32_e32 v153, v153
	v_exp_f32_e32 v154, v154
	v_exp_f32_e32 v155, v155
	v_cndmask_b32_e64 v152, 0, v152, s[54:55]
	v_cndmask_b32_e64 v153, 0, v153, s[56:57]
	v_cndmask_b32_e64 v154, 0, v154, s[58:59]
	v_cndmask_b32_e64 v155, 0, v155, s[60:61]
	v_pk_add_f32 v[138:139], v[138:139], v[152:153]
	v_pk_add_f32 v[138:139], v[138:139], v[154:155]
	v_cvt_pk_bf16_f32 v112, v152, v153
	v_cvt_pk_bf16_f32 v113, v154, v155
	s_add_i32 s77, s40, -48
	s_cmp_lt_u32 s77, s44
	s_cselect_b32 s76, s70, s71
	v_min_f32_e32 v152, s76, v240
	v_min_f32_e32 v153, s76, v241
	v_min_f32_e32 v154, s76, v242
	v_min_f32_e32 v155, s76, v243
	v_min_f32_e32 v156, s76, v248
	v_min_f32_e32 v157, s76, v249
	v_min_f32_e32 v158, s76, v250
	v_min_f32_e32 v159, s76, v251
	v_mfma_f32_16x16x32_bf16 v[240:243], v[228:231], v[48:51], 0
	v_mfma_f32_16x16x32_bf16 v[240:243], v[232:235], v[52:55], v[240:243]
	v_mfma_f32_16x16x32_bf16 v[248:251], v[228:231], v[56:59], 0
	v_mfma_f32_16x16x32_bf16 v[248:251], v[232:235], v[60:63], v[248:251]
	ds_read_b128 v[212:215], v149 offset:11520
	ds_read_b128 v[216:219], v149 offset:11584
	v_pk_mul_f32 v[152:153], v[152:153], s[72:73]
	v_pk_mul_f32 v[154:155], v[154:155], s[72:73]
	v_exp_f32_e32 v152, v152
	v_exp_f32_e32 v153, v153
	v_exp_f32_e32 v154, v154
	v_exp_f32_e32 v155, v155
	v_pk_add_f32 v[138:139], v[138:139], v[152:153]
	v_pk_add_f32 v[138:139], v[138:139], v[154:155]
	v_cvt_pk_bf16_f32 v114, v152, v153
	v_cvt_pk_bf16_f32 v115, v154, v155
	v_pk_mul_f32 v[156:157], v[156:157], s[72:73]
	v_pk_mul_f32 v[158:159], v[158:159], s[72:73]
	v_exp_f32_e32 v156, v156
	v_exp_f32_e32 v157, v157
	v_exp_f32_e32 v158, v158
	v_exp_f32_e32 v159, v159
	v_cndmask_b32_e64 v156, 0, v156, s[54:55]
	v_cndmask_b32_e64 v157, 0, v157, s[56:57]
	v_cndmask_b32_e64 v158, 0, v158, s[58:59]
	v_cndmask_b32_e64 v159, 0, v159, s[60:61]
	v_pk_add_f32 v[140:141], v[140:141], v[156:157]
	v_pk_add_f32 v[140:141], v[140:141], v[158:159]
	v_cvt_pk_bf16_f32 v186, v156, v157
	v_cvt_pk_bf16_f32 v187, v158, v159
	s_add_i32 s77, s40, -32
	s_cmp_lt_u32 s77, s44
	s_cselect_b32 s76, s70, s71
	v_min_f32_e32 v152, s76, v236
	v_min_f32_e32 v153, s76, v237
	v_min_f32_e32 v154, s76, v238
	v_min_f32_e32 v155, s76, v239
	v_min_f32_e32 v156, s76, v244
	v_min_f32_e32 v157, s76, v245
	v_min_f32_e32 v158, s76, v246
	v_min_f32_e32 v159, s76, v247
	s_waitcnt lgkmcnt(2)
	v_mfma_f32_16x16x32_bf16 v[236:239], v[204:207], v[48:51], 0
	v_mfma_f32_16x16x32_bf16 v[236:239], v[208:211], v[52:55], v[236:239]
	v_mfma_f32_16x16x32_bf16 v[244:247], v[204:207], v[56:59], 0
	v_mfma_f32_16x16x32_bf16 v[244:247], v[208:211], v[60:63], v[244:247]
	ds_read_b128 v[220:223], v149 offset:13824
	ds_read_b128 v[224:227], v149 offset:13888
	v_pk_mul_f32 v[152:153], v[152:153], s[72:73]
	v_pk_mul_f32 v[154:155], v[154:155], s[72:73]
	v_exp_f32_e32 v152, v152
	v_exp_f32_e32 v153, v153
	v_exp_f32_e32 v154, v154
	v_exp_f32_e32 v155, v155
	v_pk_add_f32 v[138:139], v[138:139], v[152:153]
	v_pk_add_f32 v[138:139], v[138:139], v[154:155]
	v_cvt_pk_bf16_f32 v116, v152, v153
	v_cvt_pk_bf16_f32 v117, v154, v155
	v_pk_mul_f32 v[156:157], v[156:157], s[72:73]
	v_pk_mul_f32 v[158:159], v[158:159], s[72:73]
	v_exp_f32_e32 v156, v156
	v_exp_f32_e32 v157, v157
	v_exp_f32_e32 v158, v158
	v_exp_f32_e32 v159, v159
	v_pk_add_f32 v[140:141], v[140:141], v[156:157]
	v_pk_add_f32 v[140:141], v[140:141], v[158:159]
	v_cvt_pk_bf16_f32 v188, v156, v157
	v_cvt_pk_bf16_f32 v189, v158, v159
	s_add_i32 s77, s40, -16
	s_cmp_lt_u32 s77, s44
	s_cselect_b32 s76, s70, s71
	v_min_f32_e32 v152, s76, v240
	v_min_f32_e32 v153, s76, v241
	v_min_f32_e32 v154, s76, v242
	v_min_f32_e32 v155, s76, v243
	v_min_f32_e32 v156, s76, v248
	v_min_f32_e32 v157, s76, v249
	v_min_f32_e32 v158, s76, v250
	v_min_f32_e32 v159, s76, v251
	s_waitcnt lgkmcnt(2)
	v_mfma_f32_16x16x32_bf16 v[240:243], v[212:215], v[48:51], 0
	v_mfma_f32_16x16x32_bf16 v[240:243], v[216:219], v[52:55], v[240:243]
	v_mfma_f32_16x16x32_bf16 v[248:251], v[212:215], v[56:59], 0
	v_mfma_f32_16x16x32_bf16 v[248:251], v[216:219], v[60:63], v[248:251]
	ds_read_b128 v[228:231], v149 offset:16128
	ds_read_b128 v[232:235], v149 offset:16192
	v_pk_mul_f32 v[152:153], v[152:153], s[72:73]
	v_pk_mul_f32 v[154:155], v[154:155], s[72:73]
	v_exp_f32_e32 v152, v152
	v_exp_f32_e32 v153, v153
	v_exp_f32_e32 v154, v154
	v_exp_f32_e32 v155, v155
	v_pk_add_f32 v[138:139], v[138:139], v[152:153]
	v_pk_add_f32 v[138:139], v[138:139], v[154:155]
	v_cvt_pk_bf16_f32 v118, v152, v153
	v_cvt_pk_bf16_f32 v119, v154, v155
	v_pk_mul_f32 v[156:157], v[156:157], s[72:73]
	v_pk_mul_f32 v[158:159], v[158:159], s[72:73]
	v_exp_f32_e32 v156, v156
	v_exp_f32_e32 v157, v157
	v_exp_f32_e32 v158, v158
	v_exp_f32_e32 v159, v159
	v_pk_add_f32 v[140:141], v[140:141], v[156:157]
	v_pk_add_f32 v[140:141], v[140:141], v[158:159]
	v_cvt_pk_bf16_f32 v190, v156, v157
	v_cvt_pk_bf16_f32 v191, v158, v159
	s_add_i32 s77, s40, 0
	s_cmp_lt_u32 s77, s44
	s_cselect_b32 s76, s70, s71
	v_min_f32_e32 v152, s76, v236
	v_min_f32_e32 v153, s76, v237
	v_min_f32_e32 v154, s76, v238
	v_min_f32_e32 v155, s76, v239
	v_min_f32_e32 v156, s76, v244
	v_min_f32_e32 v157, s76, v245
	v_min_f32_e32 v158, s76, v246
	v_min_f32_e32 v159, s76, v247
	s_waitcnt lgkmcnt(2)
	v_mfma_f32_16x16x32_bf16 v[236:239], v[220:223], v[48:51], 0
	v_mfma_f32_16x16x32_bf16 v[236:239], v[224:227], v[52:55], v[236:239]
	v_mfma_f32_16x16x32_bf16 v[244:247], v[220:223], v[56:59], 0
	v_mfma_f32_16x16x32_bf16 v[244:247], v[224:227], v[60:63], v[244:247]
	ds_read_b128 v[204:207], v149 offset:18432
	ds_read_b128 v[208:211], v149 offset:18496
	v_pk_mul_f32 v[152:153], v[152:153], s[72:73]
	v_pk_mul_f32 v[154:155], v[154:155], s[72:73]
	v_exp_f32_e32 v152, v152
	v_exp_f32_e32 v153, v153
	v_exp_f32_e32 v154, v154
	v_exp_f32_e32 v155, v155
	v_pk_add_f32 v[138:139], v[138:139], v[152:153]
	v_pk_add_f32 v[138:139], v[138:139], v[154:155]
	v_cvt_pk_bf16_f32 v120, v152, v153
	v_cvt_pk_bf16_f32 v121, v154, v155
	v_pk_mul_f32 v[156:157], v[156:157], s[72:73]
	v_pk_mul_f32 v[158:159], v[158:159], s[72:73]
	v_exp_f32_e32 v156, v156
	v_exp_f32_e32 v157, v157
	v_exp_f32_e32 v158, v158
	v_exp_f32_e32 v159, v159
	v_pk_add_f32 v[140:141], v[140:141], v[156:157]
	v_pk_add_f32 v[140:141], v[140:141], v[158:159]
	v_cvt_pk_bf16_f32 v192, v156, v157
	v_cvt_pk_bf16_f32 v193, v158, v159
	s_add_i32 s77, s40, 16
	s_cmp_lt_u32 s77, s44
	s_cselect_b32 s76, s70, s71
	v_min_f32_e32 v152, s76, v240
	v_min_f32_e32 v153, s76, v241
	v_min_f32_e32 v154, s76, v242
	v_min_f32_e32 v155, s76, v243
	v_min_f32_e32 v156, s76, v248
	v_min_f32_e32 v157, s76, v249
	v_min_f32_e32 v158, s76, v250
	v_min_f32_e32 v159, s76, v251
	s_waitcnt lgkmcnt(2)
	v_mfma_f32_16x16x32_bf16 v[240:243], v[228:231], v[48:51], 0
	v_mfma_f32_16x16x32_bf16 v[240:243], v[232:235], v[52:55], v[240:243]
	v_mfma_f32_16x16x32_bf16 v[248:251], v[228:231], v[56:59], 0
	v_mfma_f32_16x16x32_bf16 v[248:251], v[232:235], v[60:63], v[248:251]
	ds_read_b128 v[212:215], v149 offset:20736
	ds_read_b128 v[216:219], v149 offset:20800
	v_pk_mul_f32 v[152:153], v[152:153], s[72:73]
	v_pk_mul_f32 v[154:155], v[154:155], s[72:73]
	v_exp_f32_e32 v152, v152
	v_exp_f32_e32 v153, v153
	v_exp_f32_e32 v154, v154
	v_exp_f32_e32 v155, v155
	v_pk_add_f32 v[138:139], v[138:139], v[152:153]
	v_pk_add_f32 v[138:139], v[138:139], v[154:155]
	v_cvt_pk_bf16_f32 v122, v152, v153
	v_cvt_pk_bf16_f32 v123, v154, v155
	v_pk_mul_f32 v[156:157], v[156:157], s[72:73]
	v_pk_mul_f32 v[158:159], v[158:159], s[72:73]
	v_exp_f32_e32 v156, v156
	v_exp_f32_e32 v157, v157
	v_exp_f32_e32 v158, v158
	v_exp_f32_e32 v159, v159
	v_pk_add_f32 v[140:141], v[140:141], v[156:157]
	v_pk_add_f32 v[140:141], v[140:141], v[158:159]
	v_cvt_pk_bf16_f32 v194, v156, v157
	v_cvt_pk_bf16_f32 v195, v158, v159
	s_add_i32 s77, s40, 32
	s_cmp_lt_u32 s77, s44
	s_cselect_b32 s76, s70, s71
	v_min_f32_e32 v152, s76, v236
	v_min_f32_e32 v153, s76, v237
	v_min_f32_e32 v154, s76, v238
	v_min_f32_e32 v155, s76, v239
	v_min_f32_e32 v156, s76, v244
	v_min_f32_e32 v157, s76, v245
	v_min_f32_e32 v158, s76, v246
	v_min_f32_e32 v159, s76, v247
	s_waitcnt lgkmcnt(2)
	v_mfma_f32_16x16x32_bf16 v[236:239], v[204:207], v[48:51], 0
	v_mfma_f32_16x16x32_bf16 v[236:239], v[208:211], v[52:55], v[236:239]
	v_mfma_f32_16x16x32_bf16 v[244:247], v[204:207], v[56:59], 0
	v_mfma_f32_16x16x32_bf16 v[244:247], v[208:211], v[60:63], v[244:247]
	v_pk_mul_f32 v[152:153], v[152:153], s[72:73]
	v_pk_mul_f32 v[154:155], v[154:155], s[72:73]
	v_exp_f32_e32 v152, v152
	v_exp_f32_e32 v153, v153
	v_exp_f32_e32 v154, v154
	v_exp_f32_e32 v155, v155
	v_pk_add_f32 v[138:139], v[138:139], v[152:153]
	v_pk_add_f32 v[138:139], v[138:139], v[154:155]
	v_cvt_pk_bf16_f32 v124, v152, v153
	v_cvt_pk_bf16_f32 v125, v154, v155
	v_pk_mul_f32 v[156:157], v[156:157], s[72:73]
	v_pk_mul_f32 v[158:159], v[158:159], s[72:73]
	v_exp_f32_e32 v156, v156
	v_exp_f32_e32 v157, v157
	v_exp_f32_e32 v158, v158
	v_exp_f32_e32 v159, v159
	v_pk_add_f32 v[140:141], v[140:141], v[156:157]
	v_pk_add_f32 v[140:141], v[140:141], v[158:159]
	v_cvt_pk_bf16_f32 v196, v156, v157
	v_cvt_pk_bf16_f32 v197, v158, v159
	s_add_i32 s77, s40, 48
	s_cmp_lt_u32 s77, s44
	s_cselect_b32 s76, s70, s71
	v_min_f32_e32 v152, s76, v240
	v_min_f32_e32 v153, s76, v241
	v_min_f32_e32 v154, s76, v242
	v_min_f32_e32 v155, s76, v243
	v_min_f32_e32 v156, s76, v248
	v_min_f32_e32 v157, s76, v249
	v_min_f32_e32 v158, s76, v250
	v_min_f32_e32 v159, s76, v251
	s_waitcnt lgkmcnt(0)
	v_mfma_f32_16x16x32_bf16 v[248:251], v[212:215], v[56:59], 0
	v_mfma_f32_16x16x32_bf16 v[248:251], v[216:219], v[60:63], v[248:251]
	v_pk_mul_f32 v[152:153], v[152:153], s[72:73]
	v_pk_mul_f32 v[154:155], v[154:155], s[72:73]
	v_exp_f32_e32 v152, v152
	v_exp_f32_e32 v153, v153
	v_exp_f32_e32 v154, v154
	v_exp_f32_e32 v155, v155
	v_pk_add_f32 v[138:139], v[138:139], v[152:153]
	v_pk_add_f32 v[138:139], v[138:139], v[154:155]
	v_cvt_pk_bf16_f32 v126, v152, v153
	v_cvt_pk_bf16_f32 v127, v154, v155
	v_pk_mul_f32 v[156:157], v[156:157], s[72:73]
	v_pk_mul_f32 v[158:159], v[158:159], s[72:73]
	v_exp_f32_e32 v156, v156
	v_exp_f32_e32 v157, v157
	v_exp_f32_e32 v158, v158
	v_exp_f32_e32 v159, v159
	v_pk_add_f32 v[140:141], v[140:141], v[156:157]
	v_pk_add_f32 v[140:141], v[140:141], v[158:159]
	v_cvt_pk_bf16_f32 v198, v156, v157
	v_cvt_pk_bf16_f32 v199, v158, v159
	s_add_i32 s77, s40, 64
	s_cmp_lt_u32 s77, s44
	s_cselect_b32 s76, s70, s71
	v_min_f32_e32 v152, s76, v236
	v_min_f32_e32 v153, s76, v237
	v_min_f32_e32 v154, s76, v238
	v_min_f32_e32 v155, s76, v239
	v_min_f32_e32 v156, s76, v244
	v_min_f32_e32 v157, s76, v245
	v_min_f32_e32 v158, s76, v246
	v_min_f32_e32 v159, s76, v247
	v_pk_mul_f32 v[152:153], v[152:153], s[72:73]
	v_pk_mul_f32 v[154:155], v[154:155], s[72:73]
	v_exp_f32_e32 v152, v152
	v_exp_f32_e32 v153, v153
	v_exp_f32_e32 v154, v154
	v_exp_f32_e32 v155, v155
	v_cndmask_b32_e64 v152, 0, v152, s[62:63]
	v_cndmask_b32_e64 v153, 0, v153, s[64:65]
	v_cndmask_b32_e64 v154, 0, v154, s[66:67]
	v_cndmask_b32_e64 v155, 0, v155, s[68:69]
	v_pk_add_f32 v[138:139], v[138:139], v[152:153]
	v_pk_add_f32 v[138:139], v[138:139], v[154:155]
	v_cvt_pk_bf16_f32 v128, v152, v153
	v_cvt_pk_bf16_f32 v129, v154, v155
	v_pk_mul_f32 v[156:157], v[156:157], s[72:73]
	v_pk_mul_f32 v[158:159], v[158:159], s[72:73]
	v_exp_f32_e32 v156, v156
	v_exp_f32_e32 v157, v157
	v_exp_f32_e32 v158, v158
	v_exp_f32_e32 v159, v159
	v_pk_add_f32 v[140:141], v[140:141], v[156:157]
	v_pk_add_f32 v[140:141], v[140:141], v[158:159]
	v_cvt_pk_bf16_f32 v200, v156, v157
	v_cvt_pk_bf16_f32 v201, v158, v159
	s_add_i32 s77, s40, 80
	s_cmp_lt_u32 s77, s44
	s_cselect_b32 s76, s70, s71
	v_min_f32_e32 v156, s76, v248
	v_min_f32_e32 v157, s76, v249
	v_min_f32_e32 v158, s76, v250
	v_min_f32_e32 v159, s76, v251
	v_pk_mul_f32 v[156:157], v[156:157], s[72:73]
	v_pk_mul_f32 v[158:159], v[158:159], s[72:73]
	v_exp_f32_e32 v156, v156
	v_exp_f32_e32 v157, v157
	v_exp_f32_e32 v158, v158
	v_exp_f32_e32 v159, v159
	v_cndmask_b32_e64 v156, 0, v156, s[62:63]
	v_cndmask_b32_e64 v157, 0, v157, s[64:65]
	v_cndmask_b32_e64 v158, 0, v158, s[66:67]
	v_cndmask_b32_e64 v159, 0, v159, s[68:69]
	v_pk_add_f32 v[140:141], v[140:141], v[156:157]
	v_pk_add_f32 v[140:141], v[140:141], v[158:159]
	v_cvt_pk_bf16_f32 v202, v156, v157
	v_cvt_pk_bf16_f32 v203, v158, v159
	v_add_f32_e32 v132, v138, v139
	v_add_f32_e32 v133, v140, v141
	ds_bpermute_b32 v142, v167, v132
	ds_bpermute_b32 v143, v167, v133
	ds_read_b64_tr_b16 v[236:237], v151 offset:0
	ds_read_b64_tr_b16 v[238:239], v151 offset:2304
	ds_read_b64_tr_b16 v[240:241], v151 offset:32
	ds_read_b64_tr_b16 v[242:243], v151 offset:2336
	ds_read_b64_tr_b16 v[244:245], v151 offset:64
	ds_read_b64_tr_b16 v[246:247], v151 offset:2368
	ds_read_b64_tr_b16 v[248:249], v151 offset:96
	ds_read_b64_tr_b16 v[250:251], v151 offset:2400
	s_waitcnt lgkmcnt(0)
	v_add_f32_e32 v132, v132, v142
	v_add_f32_e32 v133, v133, v143
	ds_bpermute_b32 v142, v168, v132
	ds_bpermute_b32 v143, v168, v133
	ds_read_b64_tr_b16 v[48:49], v151 offset:4608
	ds_read_b64_tr_b16 v[50:51], v151 offset:6912
	ds_read_b64_tr_b16 v[52:53], v151 offset:4640
	ds_read_b64_tr_b16 v[54:55], v151 offset:6944
	ds_read_b64_tr_b16 v[56:57], v151 offset:4672
	ds_read_b64_tr_b16 v[58:59], v151 offset:6976
	ds_read_b64_tr_b16 v[60:61], v151 offset:4704
	ds_read_b64_tr_b16 v[62:63], v151 offset:7008
	v_mfma_f32_16x16x32_bf16 v[204:207], v[236:239], v[112:115], 0
	v_mfma_f32_16x16x32_bf16 v[208:211], v[240:243], v[112:115], 0
	v_mfma_f32_16x16x32_bf16 v[212:215], v[244:247], v[112:115], 0
	v_mfma_f32_16x16x32_bf16 v[216:219], v[248:251], v[112:115], 0
	v_mfma_f32_16x16x32_bf16 v[220:223], v[236:239], v[184:187], 0
	v_mfma_f32_16x16x32_bf16 v[224:227], v[240:243], v[184:187], 0
	v_mfma_f32_16x16x32_bf16 v[228:231], v[244:247], v[184:187], 0
	v_mfma_f32_16x16x32_bf16 v[232:235], v[248:251], v[184:187], 0
	s_waitcnt lgkmcnt(0)
	v_add_f32_e32 v132, v132, v142
	v_add_f32_e32 v133, v133, v143
	ds_read_b64_tr_b16 v[236:237], v151 offset:9216
	ds_read_b64_tr_b16 v[238:239], v151 offset:11520
	ds_read_b64_tr_b16 v[240:241], v151 offset:9248
	ds_read_b64_tr_b16 v[242:243], v151 offset:11552
	ds_read_b64_tr_b16 v[244:245], v151 offset:9280
	ds_read_b64_tr_b16 v[246:247], v151 offset:11584
	ds_read_b64_tr_b16 v[248:249], v151 offset:9312
	ds_read_b64_tr_b16 v[250:251], v151 offset:11616
	v_mfma_f32_16x16x32_bf16 v[204:207], v[48:51], v[116:119], v[204:207]
	v_mfma_f32_16x16x32_bf16 v[208:211], v[52:55], v[116:119], v[208:211]
	v_mfma_f32_16x16x32_bf16 v[212:215], v[56:59], v[116:119], v[212:215]
	v_mfma_f32_16x16x32_bf16 v[216:219], v[60:63], v[116:119], v[216:219]
	v_mfma_f32_16x16x32_bf16 v[220:223], v[48:51], v[188:191], v[220:223]
	v_mfma_f32_16x16x32_bf16 v[224:227], v[52:55], v[188:191], v[224:227]
	v_mfma_f32_16x16x32_bf16 v[228:231], v[56:59], v[188:191], v[228:231]
	v_mfma_f32_16x16x32_bf16 v[232:235], v[60:63], v[188:191], v[232:235]
	s_waitcnt lgkmcnt(0)
	ds_read_b64_tr_b16 v[48:49], v151 offset:13824
	ds_read_b64_tr_b16 v[50:51], v151 offset:16128
	ds_read_b64_tr_b16 v[52:53], v151 offset:13856
	ds_read_b64_tr_b16 v[54:55], v151 offset:16160
	ds_read_b64_tr_b16 v[56:57], v151 offset:13888
	ds_read_b64_tr_b16 v[58:59], v151 offset:16192
	ds_read_b64_tr_b16 v[60:61], v151 offset:13920
	ds_read_b64_tr_b16 v[62:63], v151 offset:16224
	v_mfma_f32_16x16x32_bf16 v[204:207], v[236:239], v[120:123], v[204:207]
	v_mfma_f32_16x16x32_bf16 v[208:211], v[240:243], v[120:123], v[208:211]
	v_mfma_f32_16x16x32_bf16 v[212:215], v[244:247], v[120:123], v[212:215]
	v_mfma_f32_16x16x32_bf16 v[216:219], v[248:251], v[120:123], v[216:219]
	v_mfma_f32_16x16x32_bf16 v[220:223], v[236:239], v[192:195], v[220:223]
	v_mfma_f32_16x16x32_bf16 v[224:227], v[240:243], v[192:195], v[224:227]
	v_mfma_f32_16x16x32_bf16 v[228:231], v[244:247], v[192:195], v[228:231]
	v_mfma_f32_16x16x32_bf16 v[232:235], v[248:251], v[192:195], v[232:235]
	s_waitcnt lgkmcnt(0)
	ds_read_b64_tr_b16 v[236:237], v151 offset:18432
	ds_read_b64_tr_b16 v[238:239], v151 offset:20736
	ds_read_b64_tr_b16 v[240:241], v151 offset:18464
	ds_read_b64_tr_b16 v[242:243], v151 offset:20768
	ds_read_b64_tr_b16 v[244:245], v151 offset:18496
	ds_read_b64_tr_b16 v[246:247], v151 offset:20800
	ds_read_b64_tr_b16 v[248:249], v151 offset:18528
	ds_read_b64_tr_b16 v[250:251], v151 offset:20832
	v_mfma_f32_16x16x32_bf16 v[204:207], v[48:51], v[124:127], v[204:207]
	v_mfma_f32_16x16x32_bf16 v[208:211], v[52:55], v[124:127], v[208:211]
	v_mfma_f32_16x16x32_bf16 v[212:215], v[56:59], v[124:127], v[212:215]
	v_mfma_f32_16x16x32_bf16 v[216:219], v[60:63], v[124:127], v[216:219]
	v_mfma_f32_16x16x32_bf16 v[220:223], v[48:51], v[196:199], v[220:223]
	v_mfma_f32_16x16x32_bf16 v[224:227], v[52:55], v[196:199], v[224:227]
	v_mfma_f32_16x16x32_bf16 v[228:231], v[56:59], v[196:199], v[228:231]
	v_mfma_f32_16x16x32_bf16 v[232:235], v[60:63], v[196:199], v[232:235]
	s_waitcnt lgkmcnt(0)
	v_mfma_f32_16x16x32_bf16 v[204:207], v[236:239], v[128:131], v[204:207]
	v_mfma_f32_16x16x32_bf16 v[208:211], v[240:243], v[128:131], v[208:211]
	v_mfma_f32_16x16x32_bf16 v[212:215], v[244:247], v[128:131], v[212:215]
	v_mfma_f32_16x16x32_bf16 v[216:219], v[248:251], v[128:131], v[216:219]
	v_mfma_f32_16x16x32_bf16 v[220:223], v[236:239], v[200:203], v[220:223]
	v_mfma_f32_16x16x32_bf16 v[224:227], v[240:243], v[200:203], v[224:227]
	v_mfma_f32_16x16x32_bf16 v[228:231], v[244:247], v[200:203], v[228:231]
	v_mfma_f32_16x16x32_bf16 v[232:235], v[248:251], v[200:203], v[232:235]
	s_barrier
	s_add_i32 s2, s42, 32
	v_add_u32_e32 v136, s2, v164
	v_ashrrev_i32_e32 v136, 2, v136
	v_med3_i32 v136, v136, 0, s14
	v_lshl_add_u32 v136, v136, 9, v178
	global_load_dwordx4 v[120:123], v136, s[86:87]
	s_add_i32 s2, s42, 40
	v_add_u32_e32 v135, s2, v164
	v_ashrrev_i32_e32 v135, 2, v135
	v_med3_i32 v135, v135, 0, s14
	v_lshl_add_u32 v135, v135, 9, v178
	global_load_dwordx4 v[124:127], v135, s[86:87]
	s_add_i32 s2, s42, 48
	v_add_u32_e32 v136, s2, v164
	v_ashrrev_i32_e32 v136, 2, v136
	v_med3_i32 v136, v136, 0, s14
	v_lshl_add_u32 v136, v136, 9, v178
	global_load_dwordx4 v[192:195], v136, s[86:87]
	s_add_i32 s2, s42, 56
	v_add_u32_e32 v135, s2, v164
	v_ashrrev_i32_e32 v135, 2, v135
	v_med3_i32 v135, v135, 0, s14
	v_lshl_add_u32 v135, v135, 9, v178
	global_load_dwordx4 v[196:199], v135, s[86:87]
	ds_write_b128 v173, v[204:207] offset:0
	ds_write_b128 v173, v[208:211] offset:64
	ds_write_b128 v173, v[212:215] offset:128
	ds_write_b128 v173, v[216:219] offset:192
	ds_write_b32 v174, v132 offset:0
	ds_write_b128 v173, v[220:223] offset:4624
	ds_write_b128 v173, v[224:227] offset:4688
	ds_write_b128 v173, v[228:231] offset:4752
	ds_write_b128 v173, v[232:235] offset:4816
	ds_write_b32 v174, v133 offset:64
	s_waitcnt lgkmcnt(0)
	s_barrier
	s_mov_b32 s40, s42
	s_mov_b32 s41, s43
	v_mov_b32_e32 v173, v176
	v_mov_b32_e32 v174, v177
	s_lshr_b32 s44, s33, 2
	s_lshr_b32 s42, s15, 4
	s_add_i32 s43, s0, 0
	v_subrev_u32_e32 v143, s80, v174
	v_lshl_add_u32 v143, v143, 5, v161
	v_add_u32_e32 v143, 0x1b500, v143
	ds_read_b128 v[48:51], v143
	ds_read_b128 v[52:55], v143 offset:64
	ds_read_b128 v[56:59], v143 offset:8192
	ds_read_b128 v[60:63], v143 offset:8256
	s_waitcnt lgkmcnt(0)
	v_mov_b32_e32 v138, 0
	v_mov_b32_e32 v139, 0
	v_mov_b32_e32 v140, 0
	v_mov_b32_e32 v141, 0
	s_waitcnt vmcnt(24)
	ds_write_b128 v165, v[0:3]
	ds_write_b128 v165, v[4:7] offset:1152
	ds_write_b128 v165, v[8:11] offset:2304
	ds_write_b128 v165, v[12:15] offset:3456
	s_waitcnt lgkmcnt(0)
	ds_read_b128 v[204:207], v175
	ds_read_b128 v[208:211], v175 offset:64
	ds_read_b128 v[212:215], v175 offset:2304
	ds_read_b128 v[216:219], v175 offset:2368
	s_lshl_b32 s2, s41, s39
	s_lshl_b32 s2, s2, 7
	s_add_u32 s86, s24, s2
	s_addc_u32 s87, s25, 0
	s_add_i32 s2, s40, 64
	v_add_u32_e32 v136, s2, v164
	v_ashrrev_i32_e32 v136, 2, v136
	v_med3_i32 v136, v136, 0, s38
	v_lshl_add_u32 v136, v136, 9, v178
	global_load_dwordx4 v[0:3], v136, s[86:87]
	s_add_i32 s2, s40, 72
	v_add_u32_e32 v135, s2, v164
	v_ashrrev_i32_e32 v135, 2, v135
	v_med3_i32 v135, v135, 0, s38
	v_lshl_add_u32 v135, v135, 9, v178
	global_load_dwordx4 v[4:7], v135, s[86:87]
	s_add_i32 s2, s40, 80
	v_add_u32_e32 v136, s2, v164
	v_ashrrev_i32_e32 v136, 2, v136
	v_med3_i32 v136, v136, 0, s38
	v_lshl_add_u32 v136, v136, 9, v178
	global_load_dwordx4 v[8:11], v136, s[86:87]
	s_add_i32 s2, s40, 88
	v_add_u32_e32 v135, s2, v164
	v_ashrrev_i32_e32 v135, 2, v135
	v_med3_i32 v135, v135, 0, s38
	v_lshl_add_u32 v135, v135, 9, v178
	global_load_dwordx4 v[12:15], v135, s[86:87]
	s_waitcnt vmcnt(24)
	s_waitcnt lgkmcnt(0)
	ds_write_b128 v165, v[16:19]
	ds_write_b128 v165, v[20:23] offset:1152
	ds_write_b128 v165, v[24:27] offset:2304
	ds_write_b128 v165, v[28:31] offset:3456
	v_mfma_f32_16x16x32_bf16 v[236:239], v[204:207], v[48:51], 0
	v_mfma_f32_16x16x32_bf16 v[236:239], v[208:211], v[52:55], v[236:239]
	v_mfma_f32_16x16x32_bf16 v[240:243], v[212:215], v[48:51], 0
	v_mfma_f32_16x16x32_bf16 v[240:243], v[216:219], v[52:55], v[240:243]
	v_mfma_f32_16x16x32_bf16 v[248:251], v[212:215], v[56:59], 0
	v_mfma_f32_16x16x32_bf16 v[248:251], v[216:219], v[60:63], v[248:251]
	s_waitcnt lgkmcnt(0)
	ds_read_b128 v[220:223], v175
	ds_read_b128 v[224:227], v175 offset:64
	s_lshl_b32 s2, s41, s39
	s_lshl_b32 s2, s2, 7
	s_add_u32 s74, s26, s2
	s_addc_u32 s75, s27, 0
	s_add_i32 s2, s40, 32
	v_add_u32_e32 v137, s2, v164
	v_ashrrev_i32_e32 v137, 2, v137
	v_med3_i32 v137, v137, 0, s38
	v_lshl_add_u32 v137, v137, 9, v178
	global_load_dwordx4 v[16:19], v137, s[74:75]
	s_add_i32 s2, s40, 40
	v_add_u32_e32 v137, s2, v164
	v_ashrrev_i32_e32 v137, 2, v137
	v_med3_i32 v137, v137, 0, s38
	v_lshl_add_u32 v137, v137, 9, v178
	global_load_dwordx4 v[20:23], v137, s[74:75]
	s_add_i32 s2, s40, 48
	v_add_u32_e32 v137, s2, v164
	v_ashrrev_i32_e32 v137, 2, v137
	v_med3_i32 v137, v137, 0, s38
	v_lshl_add_u32 v137, v137, 9, v178
	global_load_dwordx4 v[24:27], v137, s[74:75]
	s_add_i32 s2, s40, 56
	v_add_u32_e32 v137, s2, v164
	v_ashrrev_i32_e32 v137, 2, v137
	v_med3_i32 v137, v137, 0, s38
	v_lshl_add_u32 v137, v137, 9, v178
	global_load_dwordx4 v[28:31], v137, s[74:75]
	s_nop 7
	s_add_i32 s77, s40, -64
	s_cmp_lt_u32 s77, s44
	s_cselect_b32 s76, s70, s71
	v_min_f32_e32 v152, s76, v236
	v_min_f32_e32 v153, s76, v237
	v_min_f32_e32 v154, s76, v238
	v_min_f32_e32 v155, s76, v239
	s_waitcnt lgkmcnt(0)
	v_mfma_f32_16x16x32_bf16 v[236:239], v[220:223], v[48:51], 0
	v_mfma_f32_16x16x32_bf16 v[236:239], v[224:227], v[52:55], v[236:239]
	v_mfma_f32_16x16x32_bf16 v[244:247], v[220:223], v[56:59], 0
	v_mfma_f32_16x16x32_bf16 v[244:247], v[224:227], v[60:63], v[244:247]
	s_waitcnt vmcnt(26)
	ds_write_b128 v165, v[32:35]
	ds_write_b128 v165, v[36:39] offset:1152
	ds_read_b128 v[228:231], v175 offset:2304
	ds_read_b128 v[232:235], v175 offset:2368
	v_pk_mul_f32 v[152:153], v[152:153], s[72:73]
	v_pk_mul_f32 v[154:155], v[154:155], s[72:73]
	v_exp_f32_e32 v152, v152
	v_exp_f32_e32 v153, v153
	v_exp_f32_e32 v154, v154
	v_exp_f32_e32 v155, v155
	v_cndmask_b32_e64 v152, 0, v152, s[54:55]
	v_cndmask_b32_e64 v153, 0, v153, s[56:57]
	v_cndmask_b32_e64 v154, 0, v154, s[58:59]
	v_cndmask_b32_e64 v155, 0, v155, s[60:61]
	v_pk_add_f32 v[138:139], v[138:139], v[152:153]
	v_pk_add_f32 v[138:139], v[138:139], v[154:155]
	v_cvt_pk_bf16_f32 v112, v152, v153
	v_cvt_pk_bf16_f32 v113, v154, v155
	s_add_i32 s77, s40, -48
	s_cmp_lt_u32 s77, s44
	s_cselect_b32 s76, s70, s71
	v_min_f32_e32 v152, s76, v240
	v_min_f32_e32 v153, s76, v241
	v_min_f32_e32 v154, s76, v242
	v_min_f32_e32 v155, s76, v243
	v_min_f32_e32 v156, s76, v248
	v_min_f32_e32 v157, s76, v249
	v_min_f32_e32 v158, s76, v250
	v_min_f32_e32 v159, s76, v251
	s_waitcnt lgkmcnt(0)
	v_mfma_f32_16x16x32_bf16 v[240:243], v[228:231], v[48:51], 0
	v_mfma_f32_16x16x32_bf16 v[240:243], v[232:235], v[52:55], v[240:243]
	v_mfma_f32_16x16x32_bf16 v[248:251], v[228:231], v[56:59], 0
	v_mfma_f32_16x16x32_bf16 v[248:251], v[232:235], v[60:63], v[248:251]
	s_waitcnt vmcnt(24)
	ds_write_b128 v165, v[40:43] offset:2304
	ds_write_b128 v165, v[44:47] offset:3456
	ds_read_b128 v[204:207], v175
	ds_read_b128 v[208:211], v175 offset:64
	v_pk_mul_f32 v[152:153], v[152:153], s[72:73]
	v_pk_mul_f32 v[154:155], v[154:155], s[72:73]
	v_exp_f32_e32 v152, v152
	v_exp_f32_e32 v153, v153
	v_exp_f32_e32 v154, v154
	v_exp_f32_e32 v155, v155
	v_pk_add_f32 v[138:139], v[138:139], v[152:153]
	v_pk_add_f32 v[138:139], v[138:139], v[154:155]
	v_cvt_pk_bf16_f32 v114, v152, v153
	v_cvt_pk_bf16_f32 v115, v154, v155
	v_pk_mul_f32 v[156:157], v[156:157], s[72:73]
	v_pk_mul_f32 v[158:159], v[158:159], s[72:73]
	v_exp_f32_e32 v156, v156
	v_exp_f32_e32 v157, v157
	v_exp_f32_e32 v158, v158
	v_exp_f32_e32 v159, v159
	v_cndmask_b32_e64 v156, 0, v156, s[54:55]
	v_cndmask_b32_e64 v157, 0, v157, s[56:57]
	v_cndmask_b32_e64 v158, 0, v158, s[58:59]
	v_cndmask_b32_e64 v159, 0, v159, s[60:61]
	v_pk_add_f32 v[140:141], v[140:141], v[156:157]
	v_pk_add_f32 v[140:141], v[140:141], v[158:159]
	v_cvt_pk_bf16_f32 v186, v156, v157
	v_cvt_pk_bf16_f32 v187, v158, v159
	s_add_i32 s77, s40, -32
	s_cmp_lt_u32 s77, s44
	s_cselect_b32 s76, s70, s71
	v_min_f32_e32 v152, s76, v236
	v_min_f32_e32 v153, s76, v237
	v_min_f32_e32 v154, s76, v238
	v_min_f32_e32 v155, s76, v239
	v_min_f32_e32 v156, s76, v244
	v_min_f32_e32 v157, s76, v245
	v_min_f32_e32 v158, s76, v246
	v_min_f32_e32 v159, s76, v247
	s_waitcnt lgkmcnt(0)
	v_mfma_f32_16x16x32_bf16 v[236:239], v[204:207], v[48:51], 0
	v_mfma_f32_16x16x32_bf16 v[236:239], v[208:211], v[52:55], v[236:239]
	v_mfma_f32_16x16x32_bf16 v[244:247], v[204:207], v[56:59], 0
	v_mfma_f32_16x16x32_bf16 v[244:247], v[208:211], v[60:63], v[244:247]
	s_lshl_b32 s2, s41, s39
	s_lshl_b32 s2, s2, 7
	s_add_u32 s74, s26, s2
	s_addc_u32 s75, s27, 0
	s_add_i32 s2, s40, 64
	v_add_u32_e32 v137, s2, v164
	v_ashrrev_i32_e32 v137, 2, v137
	v_med3_i32 v137, v137, 0, s38
	v_lshl_add_u32 v137, v137, 9, v178
	global_load_dwordx4 v[32:35], v137, s[74:75]
	s_add_i32 s2, s40, 72
	v_add_u32_e32 v137, s2, v164
	v_ashrrev_i32_e32 v137, 2, v137
	v_med3_i32 v137, v137, 0, s38
	v_lshl_add_u32 v137, v137, 9, v178
	global_load_dwordx4 v[36:39], v137, s[74:75]
	s_add_i32 s2, s40, 80
	v_add_u32_e32 v137, s2, v164
	v_ashrrev_i32_e32 v137, 2, v137
	v_med3_i32 v137, v137, 0, s38
	v_lshl_add_u32 v137, v137, 9, v178
	global_load_dwordx4 v[40:43], v137, s[74:75]
	s_add_i32 s2, s40, 88
	v_add_u32_e32 v137, s2, v164
	v_ashrrev_i32_e32 v137, 2, v137
	v_med3_i32 v137, v137, 0, s38
	v_lshl_add_u32 v137, v137, 9, v178
	global_load_dwordx4 v[44:47], v137, s[74:75]
	s_waitcnt vmcnt(14)
	ds_write_b128 v165, v[120:123]
	ds_write_b128 v165, v[124:127] offset:1152
	ds_read_b128 v[212:215], v175 offset:2304
	ds_read_b128 v[216:219], v175 offset:2368
	v_pk_mul_f32 v[152:153], v[152:153], s[72:73]
	v_pk_mul_f32 v[154:155], v[154:155], s[72:73]
	v_exp_f32_e32 v152, v152
	v_exp_f32_e32 v153, v153
	v_exp_f32_e32 v154, v154
	v_exp_f32_e32 v155, v155
	v_pk_add_f32 v[138:139], v[138:139], v[152:153]
	v_pk_add_f32 v[138:139], v[138:139], v[154:155]
	v_cvt_pk_bf16_f32 v116, v152, v153
	v_cvt_pk_bf16_f32 v117, v154, v155
	v_pk_mul_f32 v[156:157], v[156:157], s[72:73]
	v_pk_mul_f32 v[158:159], v[158:159], s[72:73]
	v_exp_f32_e32 v156, v156
	v_exp_f32_e32 v157, v157
	v_exp_f32_e32 v158, v158
	v_exp_f32_e32 v159, v159
	v_pk_add_f32 v[140:141], v[140:141], v[156:157]
	v_pk_add_f32 v[140:141], v[140:141], v[158:159]
	v_cvt_pk_bf16_f32 v188, v156, v157
	v_cvt_pk_bf16_f32 v189, v158, v159
	s_add_i32 s77, s40, -16
	s_cmp_lt_u32 s77, s44
	s_cselect_b32 s76, s70, s71
	v_min_f32_e32 v152, s76, v240
	v_min_f32_e32 v153, s76, v241
	v_min_f32_e32 v154, s76, v242
	v_min_f32_e32 v155, s76, v243
	v_min_f32_e32 v156, s76, v248
	v_min_f32_e32 v157, s76, v249
	v_min_f32_e32 v158, s76, v250
	v_min_f32_e32 v159, s76, v251
	s_waitcnt lgkmcnt(0)
	v_mfma_f32_16x16x32_bf16 v[240:243], v[212:215], v[48:51], 0
	v_mfma_f32_16x16x32_bf16 v[240:243], v[216:219], v[52:55], v[240:243]
	v_mfma_f32_16x16x32_bf16 v[248:251], v[212:215], v[56:59], 0
	v_mfma_f32_16x16x32_bf16 v[248:251], v[216:219], v[60:63], v[248:251]
	s_waitcnt vmcnt(12)
	ds_write_b128 v165, v[192:195] offset:2304
	ds_write_b128 v165, v[196:199] offset:3456
	ds_read_b128 v[220:223], v175
	ds_read_b128 v[224:227], v175 offset:64
	v_pk_mul_f32 v[152:153], v[152:153], s[72:73]
	v_pk_mul_f32 v[154:155], v[154:155], s[72:73]
	v_exp_f32_e32 v152, v152
	v_exp_f32_e32 v153, v153
	v_exp_f32_e32 v154, v154
	v_exp_f32_e32 v155, v155
	v_pk_add_f32 v[138:139], v[138:139], v[152:153]
	v_pk_add_f32 v[138:139], v[138:139], v[154:155]
	v_cvt_pk_bf16_f32 v118, v152, v153
	v_cvt_pk_bf16_f32 v119, v154, v155
	v_pk_mul_f32 v[156:157], v[156:157], s[72:73]
	v_pk_mul_f32 v[158:159], v[158:159], s[72:73]
	v_exp_f32_e32 v156, v156
	v_exp_f32_e32 v157, v157
	v_exp_f32_e32 v158, v158
	v_exp_f32_e32 v159, v159
	v_pk_add_f32 v[140:141], v[140:141], v[156:157]
	v_pk_add_f32 v[140:141], v[140:141], v[158:159]
	v_cvt_pk_bf16_f32 v190, v156, v157
	v_cvt_pk_bf16_f32 v191, v158, v159
	s_add_i32 s77, s40, 0
	s_cmp_lt_u32 s77, s44
	s_cselect_b32 s76, s70, s71
	v_min_f32_e32 v152, s76, v236
	v_min_f32_e32 v153, s76, v237
	v_min_f32_e32 v154, s76, v238
	v_min_f32_e32 v155, s76, v239
	v_min_f32_e32 v156, s76, v244
	v_min_f32_e32 v157, s76, v245
	v_min_f32_e32 v158, s76, v246
	v_min_f32_e32 v159, s76, v247
	s_waitcnt lgkmcnt(0)
	v_mfma_f32_16x16x32_bf16 v[236:239], v[220:223], v[48:51], 0
	v_mfma_f32_16x16x32_bf16 v[236:239], v[224:227], v[52:55], v[236:239]
	v_mfma_f32_16x16x32_bf16 v[244:247], v[220:223], v[56:59], 0
	v_mfma_f32_16x16x32_bf16 v[244:247], v[224:227], v[60:63], v[244:247]
	s_waitcnt vmcnt(10)
	ds_write_b128 v165, v[0:3]
	ds_write_b128 v165, v[4:7] offset:1152
	ds_read_b128 v[228:231], v175 offset:2304
	ds_read_b128 v[232:235], v175 offset:2368
	v_pk_mul_f32 v[152:153], v[152:153], s[72:73]
	v_pk_mul_f32 v[154:155], v[154:155], s[72:73]
	v_exp_f32_e32 v152, v152
	v_exp_f32_e32 v153, v153
	v_exp_f32_e32 v154, v154
	v_exp_f32_e32 v155, v155
	v_pk_add_f32 v[138:139], v[138:139], v[152:153]
	v_pk_add_f32 v[138:139], v[138:139], v[154:155]
	v_cvt_pk_bf16_f32 v120, v152, v153
	v_cvt_pk_bf16_f32 v121, v154, v155
	v_pk_mul_f32 v[156:157], v[156:157], s[72:73]
	v_pk_mul_f32 v[158:159], v[158:159], s[72:73]
	v_exp_f32_e32 v156, v156
	v_exp_f32_e32 v157, v157
	v_exp_f32_e32 v158, v158
	v_exp_f32_e32 v159, v159
	v_pk_add_f32 v[140:141], v[140:141], v[156:157]
	v_pk_add_f32 v[140:141], v[140:141], v[158:159]
	v_cvt_pk_bf16_f32 v192, v156, v157
	v_cvt_pk_bf16_f32 v193, v158, v159
	s_add_i32 s77, s40, 16
	s_cmp_lt_u32 s77, s44
	s_cselect_b32 s76, s70, s71
	v_min_f32_e32 v152, s76, v240
	v_min_f32_e32 v153, s76, v241
	v_min_f32_e32 v154, s76, v242
	v_min_f32_e32 v155, s76, v243
	v_min_f32_e32 v156, s76, v248
	v_min_f32_e32 v157, s76, v249
	v_min_f32_e32 v158, s76, v250
	v_min_f32_e32 v159, s76, v251
	s_waitcnt lgkmcnt(0)
	v_mfma_f32_16x16x32_bf16 v[240:243], v[228:231], v[48:51], 0
	v_mfma_f32_16x16x32_bf16 v[240:243], v[232:235], v[52:55], v[240:243]
	v_mfma_f32_16x16x32_bf16 v[248:251], v[228:231], v[56:59], 0
	v_mfma_f32_16x16x32_bf16 v[248:251], v[232:235], v[60:63], v[248:251]
	s_waitcnt vmcnt(8)
	ds_write_b128 v165, v[8:11] offset:2304
	ds_write_b128 v165, v[12:15] offset:3456
	ds_read_b128 v[204:207], v175
	ds_read_b128 v[208:211], v175 offset:64
	v_pk_mul_f32 v[152:153], v[152:153], s[72:73]
	v_pk_mul_f32 v[154:155], v[154:155], s[72:73]
	v_exp_f32_e32 v152, v152
	v_exp_f32_e32 v153, v153
	v_exp_f32_e32 v154, v154
	v_exp_f32_e32 v155, v155
	v_pk_add_f32 v[138:139], v[138:139], v[152:153]
	v_pk_add_f32 v[138:139], v[138:139], v[154:155]
	v_cvt_pk_bf16_f32 v122, v152, v153
	v_cvt_pk_bf16_f32 v123, v154, v155
	v_pk_mul_f32 v[156:157], v[156:157], s[72:73]
	v_pk_mul_f32 v[158:159], v[158:159], s[72:73]
	v_exp_f32_e32 v156, v156
	v_exp_f32_e32 v157, v157
	v_exp_f32_e32 v158, v158
	v_exp_f32_e32 v159, v159
	v_pk_add_f32 v[140:141], v[140:141], v[156:157]
	v_pk_add_f32 v[140:141], v[140:141], v[158:159]
	v_cvt_pk_bf16_f32 v194, v156, v157
	v_cvt_pk_bf16_f32 v195, v158, v159
	s_add_i32 s77, s40, 32
	s_cmp_lt_u32 s77, s44
	s_cselect_b32 s76, s70, s71
	v_min_f32_e32 v152, s76, v236
	v_min_f32_e32 v153, s76, v237
	v_min_f32_e32 v154, s76, v238
	v_min_f32_e32 v155, s76, v239
	v_min_f32_e32 v156, s76, v244
	v_min_f32_e32 v157, s76, v245
	v_min_f32_e32 v158, s76, v246
	v_min_f32_e32 v159, s76, v247
	s_waitcnt lgkmcnt(0)
	v_mfma_f32_16x16x32_bf16 v[236:239], v[204:207], v[48:51], 0
	v_mfma_f32_16x16x32_bf16 v[236:239], v[208:211], v[52:55], v[236:239]
	v_mfma_f32_16x16x32_bf16 v[244:247], v[204:207], v[56:59], 0
	v_mfma_f32_16x16x32_bf16 v[244:247], v[208:211], v[60:63], v[244:247]
	ds_read_b128 v[212:215], v175 offset:2304
	ds_read_b128 v[216:219], v175 offset:2368
	v_pk_mul_f32 v[152:153], v[152:153], s[72:73]
	v_pk_mul_f32 v[154:155], v[154:155], s[72:73]
	v_exp_f32_e32 v152, v152
	v_exp_f32_e32 v153, v153
	v_exp_f32_e32 v154, v154
	v_exp_f32_e32 v155, v155
	v_pk_add_f32 v[138:139], v[138:139], v[152:153]
	v_pk_add_f32 v[138:139], v[138:139], v[154:155]
	v_cvt_pk_bf16_f32 v124, v152, v153
	v_cvt_pk_bf16_f32 v125, v154, v155
	v_pk_mul_f32 v[156:157], v[156:157], s[72:73]
	v_pk_mul_f32 v[158:159], v[158:159], s[72:73]
	v_exp_f32_e32 v156, v156
	v_exp_f32_e32 v157, v157
	v_exp_f32_e32 v158, v158
	v_exp_f32_e32 v159, v159
	v_pk_add_f32 v[140:141], v[140:141], v[156:157]
	v_pk_add_f32 v[140:141], v[140:141], v[158:159]
	v_cvt_pk_bf16_f32 v196, v156, v157
	v_cvt_pk_bf16_f32 v197, v158, v159
	s_add_i32 s77, s40, 48
	s_cmp_lt_u32 s77, s44
	s_cselect_b32 s76, s70, s71
	v_min_f32_e32 v152, s76, v240
	v_min_f32_e32 v153, s76, v241
	v_min_f32_e32 v154, s76, v242
	v_min_f32_e32 v155, s76, v243
	v_min_f32_e32 v156, s76, v248
	v_min_f32_e32 v157, s76, v249
	v_min_f32_e32 v158, s76, v250
	v_min_f32_e32 v159, s76, v251
	s_waitcnt lgkmcnt(0)
	v_mfma_f32_16x16x32_bf16 v[248:251], v[212:215], v[56:59], 0
	v_mfma_f32_16x16x32_bf16 v[248:251], v[216:219], v[60:63], v[248:251]
	v_pk_mul_f32 v[152:153], v[152:153], s[72:73]
	v_pk_mul_f32 v[154:155], v[154:155], s[72:73]
	v_exp_f32_e32 v152, v152
	v_exp_f32_e32 v153, v153
	v_exp_f32_e32 v154, v154
	v_exp_f32_e32 v155, v155
	v_pk_add_f32 v[138:139], v[138:139], v[152:153]
	v_pk_add_f32 v[138:139], v[138:139], v[154:155]
	v_cvt_pk_bf16_f32 v126, v152, v153
	v_cvt_pk_bf16_f32 v127, v154, v155
	v_pk_mul_f32 v[156:157], v[156:157], s[72:73]
	v_pk_mul_f32 v[158:159], v[158:159], s[72:73]
	v_exp_f32_e32 v156, v156
	v_exp_f32_e32 v157, v157
	v_exp_f32_e32 v158, v158
	v_exp_f32_e32 v159, v159
	v_pk_add_f32 v[140:141], v[140:141], v[156:157]
	v_pk_add_f32 v[140:141], v[140:141], v[158:159]
	v_cvt_pk_bf16_f32 v198, v156, v157
	v_cvt_pk_bf16_f32 v199, v158, v159
	s_add_i32 s77, s40, 64
	s_cmp_lt_u32 s77, s44
	s_cselect_b32 s76, s70, s71
	v_min_f32_e32 v152, s76, v236
	v_min_f32_e32 v153, s76, v237
	v_min_f32_e32 v154, s76, v238
	v_min_f32_e32 v155, s76, v239
	v_min_f32_e32 v156, s76, v244
	v_min_f32_e32 v157, s76, v245
	v_min_f32_e32 v158, s76, v246
	v_min_f32_e32 v159, s76, v247
	v_pk_mul_f32 v[152:153], v[152:153], s[72:73]
	v_pk_mul_f32 v[154:155], v[154:155], s[72:73]
	v_exp_f32_e32 v152, v152
	v_exp_f32_e32 v153, v153
	v_exp_f32_e32 v154, v154
	v_exp_f32_e32 v155, v155
	v_cndmask_b32_e64 v152, 0, v152, s[62:63]
	v_cndmask_b32_e64 v153, 0, v153, s[64:65]
	v_cndmask_b32_e64 v154, 0, v154, s[66:67]
	v_cndmask_b32_e64 v155, 0, v155, s[68:69]
	v_pk_add_f32 v[138:139], v[138:139], v[152:153]
	v_pk_add_f32 v[138:139], v[138:139], v[154:155]
	v_cvt_pk_bf16_f32 v128, v152, v153
	v_cvt_pk_bf16_f32 v129, v154, v155
	v_pk_mul_f32 v[156:157], v[156:157], s[72:73]
	v_pk_mul_f32 v[158:159], v[158:159], s[72:73]
	v_exp_f32_e32 v156, v156
	v_exp_f32_e32 v157, v157
	v_exp_f32_e32 v158, v158
	v_exp_f32_e32 v159, v159
	v_pk_add_f32 v[140:141], v[140:141], v[156:157]
	v_pk_add_f32 v[140:141], v[140:141], v[158:159]
	v_cvt_pk_bf16_f32 v200, v156, v157
	v_cvt_pk_bf16_f32 v201, v158, v159
	s_add_i32 s77, s40, 80
	s_cmp_lt_u32 s77, s44
	s_cselect_b32 s76, s70, s71
	v_min_f32_e32 v156, s76, v248
	v_min_f32_e32 v157, s76, v249
	v_min_f32_e32 v158, s76, v250
	v_min_f32_e32 v159, s76, v251
	v_pk_mul_f32 v[156:157], v[156:157], s[72:73]
	v_pk_mul_f32 v[158:159], v[158:159], s[72:73]
	v_exp_f32_e32 v156, v156
	v_exp_f32_e32 v157, v157
	v_exp_f32_e32 v158, v158
	v_exp_f32_e32 v159, v159
	v_cndmask_b32_e64 v156, 0, v156, s[62:63]
	v_cndmask_b32_e64 v157, 0, v157, s[64:65]
	v_cndmask_b32_e64 v158, 0, v158, s[66:67]
	v_cndmask_b32_e64 v159, 0, v159, s[68:69]
	v_pk_add_f32 v[140:141], v[140:141], v[156:157]
	v_pk_add_f32 v[140:141], v[140:141], v[158:159]
	v_cvt_pk_bf16_f32 v202, v156, v157
	v_cvt_pk_bf16_f32 v203, v158, v159
	v_add_f32_e32 v132, v138, v139
	v_add_f32_e32 v133, v140, v141
	v_add_u32_e32 v134, s42, v160
	v_lshlrev_b32_e32 v134, 4, v134
	v_add_u32_e32 v134, s43, v134
	v_subrev_u32_e32 v135, s15, v134
	v_lshrrev_b32_e32 v136, 4, v135
	v_add_u32_e32 v136, v136, v135
	v_mad_u32_u24 v176, v136, s79, v161
	v_lshl_add_u32 v177, v135, 2, s80
	s_and_b32 s2, s43, 3
	s_lshl_b32 s2, s2, s13
	s_lshr_b32 s3, s43, 2
	s_add_i32 s2, s2, s3
	s_lshl_b32 s2, s2, 7
	s_add_u32 s86, s20, s2
	s_addc_u32 s87, s21, 0
	s_add_i32 s2, s42, -64
	v_add_u32_e32 v136, s2, v164
	v_med3_i32 v136, v136, 0, s14
	v_lshl_add_u32 v136, v136, 9, v162
	global_load_dwordx4 v[0:3], v136, s[86:87]
	s_add_i32 s2, s42, -56
	v_add_u32_e32 v135, s2, v164
	v_med3_i32 v135, v135, 0, s14
	v_lshl_add_u32 v135, v135, 9, v162
	global_load_dwordx4 v[4:7], v135, s[86:87]
	s_add_i32 s2, s42, -48
	v_add_u32_e32 v136, s2, v164
	v_med3_i32 v136, v136, 0, s14
	v_lshl_add_u32 v136, v136, 9, v162
	global_load_dwordx4 v[8:11], v136, s[86:87]
	s_add_i32 s2, s42, -40
	v_add_u32_e32 v135, s2, v164
	v_med3_i32 v135, v135, 0, s14
	v_lshl_add_u32 v135, v135, 9, v162
	global_load_dwordx4 v[12:15], v135, s[86:87]
	ds_bpermute_b32 v142, v167, v132
	ds_bpermute_b32 v143, v167, v133
	ds_write_b128 v165, v[64:67]
	ds_write_b128 v165, v[68:71] offset:1152
	ds_write_b128 v165, v[72:75] offset:2304
	ds_write_b128 v165, v[76:79] offset:3456
	s_waitcnt lgkmcnt(0)
	v_add_f32_e32 v132, v132, v142
	v_add_f32_e32 v133, v133, v143
	ds_bpermute_b32 v142, v168, v132
	ds_bpermute_b32 v143, v168, v133
	ds_read_b64_tr_b16 v[236:237], v166
	ds_read_b64_tr_b16 v[238:239], v166 offset:2304
	ds_read_b64_tr_b16 v[240:241], v166 offset:32
	ds_read_b64_tr_b16 v[242:243], v166 offset:2336
	ds_read_b64_tr_b16 v[244:245], v166 offset:64
	ds_read_b64_tr_b16 v[246:247], v166 offset:2368
	ds_read_b64_tr_b16 v[248:249], v166 offset:96
	ds_read_b64_tr_b16 v[250:251], v166 offset:2400
	s_waitcnt lgkmcnt(0)
	v_add_f32_e32 v132, v132, v142
	v_add_f32_e32 v133, v133, v143
	ds_write_b128 v165, v[80:83]
	ds_write_b128 v165, v[84:87] offset:1152
	ds_write_b128 v165, v[88:91] offset:2304
	ds_write_b128 v165, v[92:95] offset:3456
	v_mfma_f32_16x16x32_bf16 v[204:207], v[236:239], v[112:115], 0
	v_mfma_f32_16x16x32_bf16 v[208:211], v[240:243], v[112:115], 0
	v_mfma_f32_16x16x32_bf16 v[212:215], v[244:247], v[112:115], 0
	v_mfma_f32_16x16x32_bf16 v[216:219], v[248:251], v[112:115], 0
	v_mfma_f32_16x16x32_bf16 v[220:223], v[236:239], v[184:187], 0
	v_mfma_f32_16x16x32_bf16 v[224:227], v[240:243], v[184:187], 0
	v_mfma_f32_16x16x32_bf16 v[228:231], v[244:247], v[184:187], 0
	v_mfma_f32_16x16x32_bf16 v[232:235], v[248:251], v[184:187], 0
	s_waitcnt lgkmcnt(0)
	ds_read_b64_tr_b16 v[236:237], v166
	ds_read_b64_tr_b16 v[238:239], v166 offset:2304
	ds_read_b64_tr_b16 v[240:241], v166 offset:32
	ds_read_b64_tr_b16 v[242:243], v166 offset:2336
	ds_read_b64_tr_b16 v[244:245], v166 offset:64
	ds_read_b64_tr_b16 v[246:247], v166 offset:2368
	ds_read_b64_tr_b16 v[248:249], v166 offset:96
	ds_read_b64_tr_b16 v[250:251], v166 offset:2400
	s_waitcnt lgkmcnt(0)
	ds_write_b128 v165, v[96:99]
	ds_write_b128 v165, v[100:103] offset:1152
	ds_write_b128 v165, v[104:107] offset:2304
	ds_write_b128 v165, v[108:111] offset:3456
	v_mfma_f32_16x16x32_bf16 v[204:207], v[236:239], v[116:119], v[204:207]
	v_mfma_f32_16x16x32_bf16 v[208:211], v[240:243], v[116:119], v[208:211]
	v_mfma_f32_16x16x32_bf16 v[212:215], v[244:247], v[116:119], v[212:215]
	v_mfma_f32_16x16x32_bf16 v[216:219], v[248:251], v[116:119], v[216:219]
	v_mfma_f32_16x16x32_bf16 v[220:223], v[236:239], v[188:191], v[220:223]
	v_mfma_f32_16x16x32_bf16 v[224:227], v[240:243], v[188:191], v[224:227]
	v_mfma_f32_16x16x32_bf16 v[228:231], v[244:247], v[188:191], v[228:231]
	v_mfma_f32_16x16x32_bf16 v[232:235], v[248:251], v[188:191], v[232:235]
	s_waitcnt lgkmcnt(0)
	ds_read_b64_tr_b16 v[236:237], v166
	ds_read_b64_tr_b16 v[238:239], v166 offset:2304
	ds_read_b64_tr_b16 v[240:241], v166 offset:32
	ds_read_b64_tr_b16 v[242:243], v166 offset:2336
	ds_read_b64_tr_b16 v[244:245], v166 offset:64
	ds_read_b64_tr_b16 v[246:247], v166 offset:2368
	ds_read_b64_tr_b16 v[248:249], v166 offset:96
	ds_read_b64_tr_b16 v[250:251], v166 offset:2400
	s_waitcnt lgkmcnt(0)
	s_waitcnt vmcnt(8)
	ds_write_b128 v165, v[16:19]
	ds_write_b128 v165, v[20:23] offset:1152
	ds_write_b128 v165, v[24:27] offset:2304
	ds_write_b128 v165, v[28:31] offset:3456
	v_mfma_f32_16x16x32_bf16 v[204:207], v[236:239], v[120:123], v[204:207]
	v_mfma_f32_16x16x32_bf16 v[208:211], v[240:243], v[120:123], v[208:211]
	v_mfma_f32_16x16x32_bf16 v[212:215], v[244:247], v[120:123], v[212:215]
	v_mfma_f32_16x16x32_bf16 v[216:219], v[248:251], v[120:123], v[216:219]
	v_mfma_f32_16x16x32_bf16 v[220:223], v[236:239], v[192:195], v[220:223]
	v_mfma_f32_16x16x32_bf16 v[224:227], v[240:243], v[192:195], v[224:227]
	v_mfma_f32_16x16x32_bf16 v[228:231], v[244:247], v[192:195], v[228:231]
	v_mfma_f32_16x16x32_bf16 v[232:235], v[248:251], v[192:195], v[232:235]
	s_waitcnt lgkmcnt(0)
	ds_read_b64_tr_b16 v[236:237], v166
	ds_read_b64_tr_b16 v[238:239], v166 offset:2304
	ds_read_b64_tr_b16 v[240:241], v166 offset:32
	ds_read_b64_tr_b16 v[242:243], v166 offset:2336
	ds_read_b64_tr_b16 v[244:245], v166 offset:64
	ds_read_b64_tr_b16 v[246:247], v166 offset:2368
	ds_read_b64_tr_b16 v[248:249], v166 offset:96
	ds_read_b64_tr_b16 v[250:251], v166 offset:2400
	s_waitcnt lgkmcnt(0)
	s_add_i32 s2, s42, -32
	v_add_u32_e32 v136, s2, v164
	v_med3_i32 v136, v136, 0, s14
	v_lshl_add_u32 v136, v136, 9, v162
	global_load_dwordx4 v[16:19], v136, s[86:87]
	s_add_i32 s2, s42, -24
	v_add_u32_e32 v135, s2, v164
	v_med3_i32 v135, v135, 0, s14
	v_lshl_add_u32 v135, v135, 9, v162
	global_load_dwordx4 v[20:23], v135, s[86:87]
	s_add_i32 s2, s42, -16
	v_add_u32_e32 v136, s2, v164
	v_med3_i32 v136, v136, 0, s14
	v_lshl_add_u32 v136, v136, 9, v162
	global_load_dwordx4 v[24:27], v136, s[86:87]
	s_add_i32 s2, s42, -8
	v_add_u32_e32 v135, s2, v164
	v_med3_i32 v135, v135, 0, s14
	v_lshl_add_u32 v135, v135, 9, v162
	global_load_dwordx4 v[28:31], v135, s[86:87]
	s_waitcnt vmcnt(8)
	ds_write_b128 v165, v[32:35]
	ds_write_b128 v165, v[36:39] offset:1152
	ds_write_b128 v165, v[40:43] offset:2304
	ds_write_b128 v165, v[44:47] offset:3456
	v_mfma_f32_16x16x32_bf16 v[204:207], v[236:239], v[124:127], v[204:207]
	v_mfma_f32_16x16x32_bf16 v[208:211], v[240:243], v[124:127], v[208:211]
	v_mfma_f32_16x16x32_bf16 v[212:215], v[244:247], v[124:127], v[212:215]
	v_mfma_f32_16x16x32_bf16 v[216:219], v[248:251], v[124:127], v[216:219]
	v_mfma_f32_16x16x32_bf16 v[220:223], v[236:239], v[196:199], v[220:223]
	v_mfma_f32_16x16x32_bf16 v[224:227], v[240:243], v[196:199], v[224:227]
	v_mfma_f32_16x16x32_bf16 v[228:231], v[244:247], v[196:199], v[228:231]
	v_mfma_f32_16x16x32_bf16 v[232:235], v[248:251], v[196:199], v[232:235]
	s_waitcnt lgkmcnt(0)
	ds_read_b64_tr_b16 v[236:237], v166
	ds_read_b64_tr_b16 v[238:239], v166 offset:2304
	ds_read_b64_tr_b16 v[240:241], v166 offset:32
	ds_read_b64_tr_b16 v[242:243], v166 offset:2336
	ds_read_b64_tr_b16 v[244:245], v166 offset:64
	ds_read_b64_tr_b16 v[246:247], v166 offset:2368
	ds_read_b64_tr_b16 v[248:249], v166 offset:96
	ds_read_b64_tr_b16 v[250:251], v166 offset:2400
	s_waitcnt lgkmcnt(0)
	s_add_i32 s2, s42, 0
	v_add_u32_e32 v136, s2, v164
	v_med3_i32 v136, v136, 0, s14
	v_lshl_add_u32 v136, v136, 9, v162
	global_load_dwordx4 v[32:35], v136, s[86:87]
	s_add_i32 s2, s42, 8
	v_add_u32_e32 v135, s2, v164
	v_med3_i32 v135, v135, 0, s14
	v_lshl_add_u32 v135, v135, 9, v162
	global_load_dwordx4 v[36:39], v135, s[86:87]
	s_add_i32 s2, s42, 16
	v_add_u32_e32 v136, s2, v164
	v_med3_i32 v136, v136, 0, s14
	v_lshl_add_u32 v136, v136, 9, v162
	global_load_dwordx4 v[40:43], v136, s[86:87]
	s_add_i32 s2, s42, 24
	v_add_u32_e32 v135, s2, v164
	v_med3_i32 v135, v135, 0, s14
	v_lshl_add_u32 v135, v135, 9, v162
	global_load_dwordx4 v[44:47], v135, s[86:87]
	v_mfma_f32_16x16x32_bf16 v[204:207], v[236:239], v[128:131], v[204:207]
	v_mfma_f32_16x16x32_bf16 v[208:211], v[240:243], v[128:131], v[208:211]
	v_mfma_f32_16x16x32_bf16 v[212:215], v[244:247], v[128:131], v[212:215]
	v_mfma_f32_16x16x32_bf16 v[216:219], v[248:251], v[128:131], v[216:219]
	v_mfma_f32_16x16x32_bf16 v[220:223], v[236:239], v[200:203], v[220:223]
	v_mfma_f32_16x16x32_bf16 v[224:227], v[240:243], v[200:203], v[224:227]
	v_mfma_f32_16x16x32_bf16 v[228:231], v[244:247], v[200:203], v[228:231]
	v_mfma_f32_16x16x32_bf16 v[232:235], v[248:251], v[200:203], v[232:235]
	s_add_i32 s2, s42, 32
	v_add_u32_e32 v136, s2, v164
	v_med3_i32 v136, v136, 0, s14
	v_lshl_add_u32 v136, v136, 9, v162
	global_load_dwordx4 v[120:123], v136, s[86:87]
	s_add_i32 s2, s42, 40
	v_add_u32_e32 v135, s2, v164
	v_med3_i32 v135, v135, 0, s14
	v_lshl_add_u32 v135, v135, 9, v162
	global_load_dwordx4 v[124:127], v135, s[86:87]
	s_add_i32 s2, s42, 48
	v_add_u32_e32 v136, s2, v164
	v_med3_i32 v136, v136, 0, s14
	v_lshl_add_u32 v136, v136, 9, v162
	global_load_dwordx4 v[192:195], v136, s[86:87]
	s_add_i32 s2, s42, 56
	v_add_u32_e32 v135, s2, v164
	v_med3_i32 v135, v135, 0, s14
	v_lshl_add_u32 v135, v135, 9, v162
	global_load_dwordx4 v[196:199], v135, s[86:87]
	s_and_b32 s2, s43, 3
	s_lshl_b32 s2, s2, s13
	s_lshr_b32 s3, s43, 2
	s_add_i32 s2, s2, s3
	s_lshl_b32 s2, s2, 7
	s_add_u32 s74, s22, s2
	s_addc_u32 s75, s23, 0
	s_add_i32 s2, s42, -64
	v_add_u32_e32 v137, s2, v164
	v_med3_i32 v137, v137, 0, s14
	v_lshl_add_u32 v137, v137, 9, v162
	global_load_dwordx4 v[64:67], v137, s[74:75]
	s_add_i32 s2, s42, -56
	v_add_u32_e32 v137, s2, v164
	v_med3_i32 v137, v137, 0, s14
	v_lshl_add_u32 v137, v137, 9, v162
	global_load_dwordx4 v[68:71], v137, s[74:75]
	s_add_i32 s2, s42, -48
	v_add_u32_e32 v137, s2, v164
	v_med3_i32 v137, v137, 0, s14
	v_lshl_add_u32 v137, v137, 9, v162
	global_load_dwordx4 v[72:75], v137, s[74:75]
	s_add_i32 s2, s42, -40
	v_add_u32_e32 v137, s2, v164
	v_med3_i32 v137, v137, 0, s14
	v_lshl_add_u32 v137, v137, 9, v162
	global_load_dwordx4 v[76:79], v137, s[74:75]
	s_and_b32 s2, s43, 3
	s_lshl_b32 s2, s2, s13
	s_lshr_b32 s3, s43, 2
	s_add_i32 s2, s2, s3
	s_lshl_b32 s2, s2, 7
	s_add_u32 s74, s22, s2
	s_addc_u32 s75, s23, 0
	s_add_i32 s2, s42, -32
	v_add_u32_e32 v137, s2, v164
	v_med3_i32 v137, v137, 0, s14
	v_lshl_add_u32 v137, v137, 9, v162
	global_load_dwordx4 v[80:83], v137, s[74:75]
	s_add_i32 s2, s42, -24
	v_add_u32_e32 v137, s2, v164
	v_med3_i32 v137, v137, 0, s14
	v_lshl_add_u32 v137, v137, 9, v162
	global_load_dwordx4 v[84:87], v137, s[74:75]
	s_add_i32 s2, s42, -16
	v_add_u32_e32 v137, s2, v164
	v_med3_i32 v137, v137, 0, s14
	v_lshl_add_u32 v137, v137, 9, v162
	global_load_dwordx4 v[88:91], v137, s[74:75]
	s_add_i32 s2, s42, -8
	v_add_u32_e32 v137, s2, v164
	v_med3_i32 v137, v137, 0, s14
	v_lshl_add_u32 v137, v137, 9, v162
	global_load_dwordx4 v[92:95], v137, s[74:75]
	s_and_b32 s2, s43, 3
	s_lshl_b32 s2, s2, s13
	s_lshr_b32 s3, s43, 2
	s_add_i32 s2, s2, s3
	s_lshl_b32 s2, s2, 7
	s_add_u32 s74, s22, s2
	s_addc_u32 s75, s23, 0
	s_add_i32 s2, s42, 0
	v_add_u32_e32 v137, s2, v164
	v_med3_i32 v137, v137, 0, s14
	v_lshl_add_u32 v137, v137, 9, v162
	global_load_dwordx4 v[96:99], v137, s[74:75]
	s_add_i32 s2, s42, 8
	v_add_u32_e32 v137, s2, v164
	v_med3_i32 v137, v137, 0, s14
	v_lshl_add_u32 v137, v137, 9, v162
	global_load_dwordx4 v[100:103], v137, s[74:75]
	s_add_i32 s2, s42, 16
	v_add_u32_e32 v137, s2, v164
	v_med3_i32 v137, v137, 0, s14
	v_lshl_add_u32 v137, v137, 9, v162
	global_load_dwordx4 v[104:107], v137, s[74:75]
	s_add_i32 s2, s42, 24
	v_add_u32_e32 v137, s2, v164
	v_med3_i32 v137, v137, 0, s14
	v_lshl_add_u32 v137, v137, 9, v162
	global_load_dwordx4 v[108:111], v137, s[74:75]
	ds_read_b128 v[236:239], v173 offset:0
	ds_read_b128 v[240:243], v173 offset:64
	ds_read_b128 v[244:247], v173 offset:128
	ds_read_b128 v[248:251], v173 offset:192
	ds_read_b32 v142, v174 offset:0
	s_waitcnt lgkmcnt(0)
	v_add_f32_e32 v204, v236, v204
	v_add_f32_e32 v205, v237, v205
	v_add_f32_e32 v206, v238, v206
	v_add_f32_e32 v207, v239, v207
	v_add_f32_e32 v208, v240, v208
	v_add_f32_e32 v209, v241, v209
	v_add_f32_e32 v210, v242, v210
	v_add_f32_e32 v211, v243, v211
	v_add_f32_e32 v212, v244, v212
	v_add_f32_e32 v213, v245, v213
	v_add_f32_e32 v214, v246, v214
	v_add_f32_e32 v215, v247, v215
	v_add_f32_e32 v216, v248, v216
	v_add_f32_e32 v217, v249, v217
	v_add_f32_e32 v218, v250, v218
	v_add_f32_e32 v219, v251, v219
	v_add_f32_e32 v132, v142, v132
	ds_write_b128 v173, v[204:207] offset:0
	ds_write_b128 v173, v[208:211] offset:64
	ds_write_b128 v173, v[212:215] offset:128
	ds_write_b128 v173, v[216:219] offset:192
	ds_write_b32 v174, v132 offset:0
	ds_read_b128 v[236:239], v173 offset:18496
	ds_read_b128 v[240:243], v173 offset:18560
	ds_read_b128 v[244:247], v173 offset:18624
	ds_read_b128 v[248:251], v173 offset:18688
	ds_read_b32 v142, v174 offset:256
	s_waitcnt lgkmcnt(0)
	v_add_f32_e32 v220, v236, v220
	v_add_f32_e32 v221, v237, v221
	v_add_f32_e32 v222, v238, v222
	v_add_f32_e32 v223, v239, v223
	v_add_f32_e32 v224, v240, v224
	v_add_f32_e32 v225, v241, v225
	v_add_f32_e32 v226, v242, v226
	v_add_f32_e32 v227, v243, v227
	v_add_f32_e32 v228, v244, v228
	v_add_f32_e32 v229, v245, v229
	v_add_f32_e32 v230, v246, v230
	v_add_f32_e32 v231, v247, v231
	v_add_f32_e32 v232, v248, v232
	v_add_f32_e32 v233, v249, v233
	v_add_f32_e32 v234, v250, v234
	v_add_f32_e32 v235, v251, v235
	v_add_f32_e32 v133, v142, v133
	ds_write_b128 v173, v[220:223] offset:18496
	ds_write_b128 v173, v[224:227] offset:18560
	ds_write_b128 v173, v[228:231] offset:18624
	ds_write_b128 v173, v[232:235] offset:18688
	ds_write_b32 v174, v133 offset:256
	s_waitcnt lgkmcnt(0)
	s_barrier
	s_mov_b32 s40, s42
	s_mov_b32 s41, s43
	v_mov_b32_e32 v173, v176
	v_mov_b32_e32 v174, v177
	s_lshr_b32 s44, s33, 4
	s_lshr_b32 s42, s15, 4
	s_add_i32 s43, s0, 8
	v_subrev_u32_e32 v143, s80, v174
	v_lshl_add_u32 v143, v143, 5, v161
	v_add_u32_e32 v143, 0x1b500, v143
	ds_read_b128 v[48:51], v143
	ds_read_b128 v[52:55], v143 offset:64
	s_waitcnt lgkmcnt(0)
	v_mov_b32_e32 v138, 0
	v_mov_b32_e32 v139, 0
	s_waitcnt vmcnt(24)
	ds_write_b128 v165, v[0:3]
	ds_write_b128 v165, v[4:7] offset:1152
	ds_write_b128 v165, v[8:11] offset:2304
	ds_write_b128 v165, v[12:15] offset:3456
	s_waitcnt lgkmcnt(0)
	ds_read_b128 v[204:207], v175
	ds_read_b128 v[208:211], v175 offset:64
	ds_read_b128 v[212:215], v175 offset:2304
	ds_read_b128 v[216:219], v175 offset:2368
	s_and_b32 s2, s41, 3
	s_lshl_b32 s2, s2, s39
	s_lshr_b32 s3, s41, 2
	s_add_i32 s2, s2, s3
	s_lshl_b32 s2, s2, 7
	s_add_u32 s86, s24, s2
	s_addc_u32 s87, s25, 0
	s_add_i32 s2, s40, 64
	v_add_u32_e32 v136, s2, v164
	v_med3_i32 v136, v136, 0, s38
	v_lshl_add_u32 v136, v136, 9, v162
	global_load_dwordx4 v[0:3], v136, s[86:87]
	s_add_i32 s2, s40, 72
	v_add_u32_e32 v135, s2, v164
	v_med3_i32 v135, v135, 0, s38
	v_lshl_add_u32 v135, v135, 9, v162
	global_load_dwordx4 v[4:7], v135, s[86:87]
	s_waitcnt vmcnt(22)
	s_waitcnt lgkmcnt(0)
	ds_write_b128 v165, v[16:19]
	ds_write_b128 v165, v[20:23] offset:1152
	ds_write_b128 v165, v[24:27] offset:2304
	ds_write_b128 v165, v[28:31] offset:3456
	v_mfma_f32_16x16x32_bf16 v[236:239], v[204:207], v[48:51], 0
	v_mfma_f32_16x16x32_bf16 v[236:239], v[208:211], v[52:55], v[236:239]
	v_mfma_f32_16x16x32_bf16 v[240:243], v[212:215], v[48:51], 0
	v_mfma_f32_16x16x32_bf16 v[240:243], v[216:219], v[52:55], v[240:243]
	s_waitcnt lgkmcnt(0)
	ds_read_b128 v[220:223], v175
	ds_read_b128 v[224:227], v175 offset:64
	s_and_b32 s2, s41, 3
	s_lshl_b32 s2, s2, s39
	s_lshr_b32 s3, s41, 2
	s_add_i32 s2, s2, s3
	s_lshl_b32 s2, s2, 7
	s_add_u32 s74, s26, s2
	s_addc_u32 s75, s27, 0
	s_add_i32 s2, s40, 32
	v_add_u32_e32 v137, s2, v164
	v_med3_i32 v137, v137, 0, s38
	v_lshl_add_u32 v137, v137, 9, v162
	global_load_dwordx4 v[16:19], v137, s[74:75]
	s_add_i32 s2, s40, 40
	v_add_u32_e32 v137, s2, v164
	v_med3_i32 v137, v137, 0, s38
	v_lshl_add_u32 v137, v137, 9, v162
	global_load_dwordx4 v[20:23], v137, s[74:75]
	s_add_i32 s2, s40, 48
	v_add_u32_e32 v137, s2, v164
	v_med3_i32 v137, v137, 0, s38
	v_lshl_add_u32 v137, v137, 9, v162
	global_load_dwordx4 v[24:27], v137, s[74:75]
	s_add_i32 s2, s40, 56
	v_add_u32_e32 v137, s2, v164
	v_med3_i32 v137, v137, 0, s38
	v_lshl_add_u32 v137, v137, 9, v162
	global_load_dwordx4 v[28:31], v137, s[74:75]
	s_nop 7
	s_add_i32 s77, s40, -64
	s_cmp_lt_u32 s77, s44
	s_cselect_b32 s76, s70, s71
	v_min_f32_e32 v152, s76, v236
	v_min_f32_e32 v153, s76, v237
	v_min_f32_e32 v154, s76, v238
	v_min_f32_e32 v155, s76, v239
	s_waitcnt lgkmcnt(0)
	v_mfma_f32_16x16x32_bf16 v[236:239], v[220:223], v[48:51], 0
	v_mfma_f32_16x16x32_bf16 v[236:239], v[224:227], v[52:55], v[236:239]
	s_waitcnt vmcnt(24)
	ds_write_b128 v165, v[32:35]
	ds_write_b128 v165, v[36:39] offset:1152
	ds_read_b128 v[228:231], v175 offset:2304
	ds_read_b128 v[232:235], v175 offset:2368
	v_pk_mul_f32 v[152:153], v[152:153], s[72:73]
	v_pk_mul_f32 v[154:155], v[154:155], s[72:73]
	v_exp_f32_e32 v152, v152
	v_exp_f32_e32 v153, v153
	v_exp_f32_e32 v154, v154
	v_exp_f32_e32 v155, v155
	v_cndmask_b32_e64 v152, 0, v152, s[54:55]
	v_cndmask_b32_e64 v153, 0, v153, s[56:57]
	v_cndmask_b32_e64 v154, 0, v154, s[58:59]
	v_cndmask_b32_e64 v155, 0, v155, s[60:61]
	v_pk_add_f32 v[138:139], v[138:139], v[152:153]
	v_pk_add_f32 v[138:139], v[138:139], v[154:155]
	v_cvt_pk_bf16_f32 v112, v152, v153
	v_cvt_pk_bf16_f32 v113, v154, v155
	s_add_i32 s77, s40, -48
	s_cmp_lt_u32 s77, s44
	s_cselect_b32 s76, s70, s71
	v_min_f32_e32 v152, s76, v240
	v_min_f32_e32 v153, s76, v241
	v_min_f32_e32 v154, s76, v242
	v_min_f32_e32 v155, s76, v243
	s_waitcnt lgkmcnt(0)
	v_mfma_f32_16x16x32_bf16 v[240:243], v[228:231], v[48:51], 0
	v_mfma_f32_16x16x32_bf16 v[240:243], v[232:235], v[52:55], v[240:243]
	s_waitcnt vmcnt(22)
	ds_write_b128 v165, v[40:43] offset:2304
	ds_write_b128 v165, v[44:47] offset:3456
	ds_read_b128 v[204:207], v175
	ds_read_b128 v[208:211], v175 offset:64
	v_pk_mul_f32 v[152:153], v[152:153], s[72:73]
	v_pk_mul_f32 v[154:155], v[154:155], s[72:73]
	v_exp_f32_e32 v152, v152
	v_exp_f32_e32 v153, v153
	v_exp_f32_e32 v154, v154
	v_exp_f32_e32 v155, v155
	v_pk_add_f32 v[138:139], v[138:139], v[152:153]
	v_pk_add_f32 v[138:139], v[138:139], v[154:155]
	v_cvt_pk_bf16_f32 v114, v152, v153
	v_cvt_pk_bf16_f32 v115, v154, v155
	s_add_i32 s77, s40, -32
	s_cmp_lt_u32 s77, s44
	s_cselect_b32 s76, s70, s71
	v_min_f32_e32 v152, s76, v236
	v_min_f32_e32 v153, s76, v237
	v_min_f32_e32 v154, s76, v238
	v_min_f32_e32 v155, s76, v239
	s_waitcnt lgkmcnt(0)
	v_mfma_f32_16x16x32_bf16 v[236:239], v[204:207], v[48:51], 0
	v_mfma_f32_16x16x32_bf16 v[236:239], v[208:211], v[52:55], v[236:239]
	s_and_b32 s2, s41, 3
	s_lshl_b32 s2, s2, s39
	s_lshr_b32 s3, s41, 2
	s_add_i32 s2, s2, s3
	s_lshl_b32 s2, s2, 7
	s_add_u32 s74, s26, s2
	s_addc_u32 s75, s27, 0
	s_add_i32 s2, s40, 64
	v_add_u32_e32 v137, s2, v164
	v_med3_i32 v137, v137, 0, s38
	v_lshl_add_u32 v137, v137, 9, v162
	global_load_dwordx4 v[32:35], v137, s[74:75]
	s_add_i32 s2, s40, 72
	v_add_u32_e32 v137, s2, v164
	v_med3_i32 v137, v137, 0, s38
	v_lshl_add_u32 v137, v137, 9, v162
	global_load_dwordx4 v[36:39], v137, s[74:75]
	s_waitcnt vmcnt(22)
	ds_write_b128 v165, v[120:123]
	ds_write_b128 v165, v[124:127] offset:1152
	ds_read_b128 v[212:215], v175 offset:2304
	ds_read_b128 v[216:219], v175 offset:2368
	v_pk_mul_f32 v[152:153], v[152:153], s[72:73]
	v_pk_mul_f32 v[154:155], v[154:155], s[72:73]
	v_exp_f32_e32 v152, v152
	v_exp_f32_e32 v153, v153
	v_exp_f32_e32 v154, v154
	v_exp_f32_e32 v155, v155
	v_pk_add_f32 v[138:139], v[138:139], v[152:153]
	v_pk_add_f32 v[138:139], v[138:139], v[154:155]
	v_cvt_pk_bf16_f32 v116, v152, v153
	v_cvt_pk_bf16_f32 v117, v154, v155
	s_add_i32 s77, s40, -16
	s_cmp_lt_u32 s77, s44
	s_cselect_b32 s76, s70, s71
	v_min_f32_e32 v152, s76, v240
	v_min_f32_e32 v153, s76, v241
	v_min_f32_e32 v154, s76, v242
	v_min_f32_e32 v155, s76, v243
	s_waitcnt lgkmcnt(0)
	v_mfma_f32_16x16x32_bf16 v[240:243], v[212:215], v[48:51], 0
	v_mfma_f32_16x16x32_bf16 v[240:243], v[216:219], v[52:55], v[240:243]
	s_waitcnt vmcnt(20)
	ds_write_b128 v165, v[192:195] offset:2304
	ds_write_b128 v165, v[196:199] offset:3456
	ds_read_b128 v[220:223], v175
	ds_read_b128 v[224:227], v175 offset:64
	v_pk_mul_f32 v[152:153], v[152:153], s[72:73]
	v_pk_mul_f32 v[154:155], v[154:155], s[72:73]
	v_exp_f32_e32 v152, v152
	v_exp_f32_e32 v153, v153
	v_exp_f32_e32 v154, v154
	v_exp_f32_e32 v155, v155
	v_pk_add_f32 v[138:139], v[138:139], v[152:153]
	v_pk_add_f32 v[138:139], v[138:139], v[154:155]
	v_cvt_pk_bf16_f32 v118, v152, v153
	v_cvt_pk_bf16_f32 v119, v154, v155
	s_add_i32 s77, s40, 0
	s_cmp_lt_u32 s77, s44
	s_cselect_b32 s76, s70, s71
	v_min_f32_e32 v152, s76, v236
	v_min_f32_e32 v153, s76, v237
	v_min_f32_e32 v154, s76, v238
	v_min_f32_e32 v155, s76, v239
	s_waitcnt lgkmcnt(0)
	v_mfma_f32_16x16x32_bf16 v[236:239], v[220:223], v[48:51], 0
	v_mfma_f32_16x16x32_bf16 v[236:239], v[224:227], v[52:55], v[236:239]
	s_waitcnt vmcnt(6)
	ds_write_b128 v165, v[0:3]
	ds_write_b128 v165, v[4:7] offset:1152
	ds_read_b128 v[228:231], v175 offset:2304
	ds_read_b128 v[232:235], v175 offset:2368
	v_pk_mul_f32 v[152:153], v[152:153], s[72:73]
	v_pk_mul_f32 v[154:155], v[154:155], s[72:73]
	v_exp_f32_e32 v152, v152
	v_exp_f32_e32 v153, v153
	v_exp_f32_e32 v154, v154
	v_exp_f32_e32 v155, v155
	v_pk_add_f32 v[138:139], v[138:139], v[152:153]
	v_pk_add_f32 v[138:139], v[138:139], v[154:155]
	v_cvt_pk_bf16_f32 v120, v152, v153
	v_cvt_pk_bf16_f32 v121, v154, v155
	s_add_i32 s77, s40, 16
	s_cmp_lt_u32 s77, s44
	s_cselect_b32 s76, s70, s71
	v_min_f32_e32 v152, s76, v240
	v_min_f32_e32 v153, s76, v241
	v_min_f32_e32 v154, s76, v242
	v_min_f32_e32 v155, s76, v243
	s_waitcnt lgkmcnt(0)
	v_mfma_f32_16x16x32_bf16 v[240:243], v[228:231], v[48:51], 0
	v_mfma_f32_16x16x32_bf16 v[240:243], v[232:235], v[52:55], v[240:243]
	ds_read_b128 v[204:207], v175
	ds_read_b128 v[208:211], v175 offset:64
	v_pk_mul_f32 v[152:153], v[152:153], s[72:73]
	v_pk_mul_f32 v[154:155], v[154:155], s[72:73]
	v_exp_f32_e32 v152, v152
	v_exp_f32_e32 v153, v153
	v_exp_f32_e32 v154, v154
	v_exp_f32_e32 v155, v155
	v_pk_add_f32 v[138:139], v[138:139], v[152:153]
	v_pk_add_f32 v[138:139], v[138:139], v[154:155]
	v_cvt_pk_bf16_f32 v122, v152, v153
	v_cvt_pk_bf16_f32 v123, v154, v155
	s_add_i32 s77, s40, 32
	s_cmp_lt_u32 s77, s44
	s_cselect_b32 s76, s70, s71
	v_min_f32_e32 v152, s76, v236
	v_min_f32_e32 v153, s76, v237
	v_min_f32_e32 v154, s76, v238
	v_min_f32_e32 v155, s76, v239
	s_waitcnt lgkmcnt(0)
	v_mfma_f32_16x16x32_bf16 v[236:239], v[204:207], v[48:51], 0
	v_mfma_f32_16x16x32_bf16 v[236:239], v[208:211], v[52:55], v[236:239]
	v_pk_mul_f32 v[152:153], v[152:153], s[72:73]
	v_pk_mul_f32 v[154:155], v[154:155], s[72:73]
	v_exp_f32_e32 v152, v152
	v_exp_f32_e32 v153, v153
	v_exp_f32_e32 v154, v154
	v_exp_f32_e32 v155, v155
	v_pk_add_f32 v[138:139], v[138:139], v[152:153]
	v_pk_add_f32 v[138:139], v[138:139], v[154:155]
	v_cvt_pk_bf16_f32 v124, v152, v153
	v_cvt_pk_bf16_f32 v125, v154, v155
	s_add_i32 s77, s40, 48
	s_cmp_lt_u32 s77, s44
	s_cselect_b32 s76, s70, s71
	v_min_f32_e32 v152, s76, v240
	v_min_f32_e32 v153, s76, v241
	v_min_f32_e32 v154, s76, v242
	v_min_f32_e32 v155, s76, v243
	v_pk_mul_f32 v[152:153], v[152:153], s[72:73]
	v_pk_mul_f32 v[154:155], v[154:155], s[72:73]
	v_exp_f32_e32 v152, v152
	v_exp_f32_e32 v153, v153
	v_exp_f32_e32 v154, v154
	v_exp_f32_e32 v155, v155
	v_pk_add_f32 v[138:139], v[138:139], v[152:153]
	v_pk_add_f32 v[138:139], v[138:139], v[154:155]
	v_cvt_pk_bf16_f32 v126, v152, v153
	v_cvt_pk_bf16_f32 v127, v154, v155
	s_add_i32 s77, s40, 64
	s_cmp_lt_u32 s77, s44
	s_cselect_b32 s76, s70, s71
	v_min_f32_e32 v152, s76, v236
	v_min_f32_e32 v153, s76, v237
	v_min_f32_e32 v154, s76, v238
	v_min_f32_e32 v155, s76, v239
	v_pk_mul_f32 v[152:153], v[152:153], s[72:73]
	v_pk_mul_f32 v[154:155], v[154:155], s[72:73]
	v_exp_f32_e32 v152, v152
	v_exp_f32_e32 v153, v153
	v_exp_f32_e32 v154, v154
	v_exp_f32_e32 v155, v155
	v_cndmask_b32_e64 v152, 0, v152, s[62:63]
	v_cndmask_b32_e64 v153, 0, v153, s[64:65]
	v_cndmask_b32_e64 v154, 0, v154, s[66:67]
	v_cndmask_b32_e64 v155, 0, v155, s[68:69]
	v_pk_add_f32 v[138:139], v[138:139], v[152:153]
	v_pk_add_f32 v[138:139], v[138:139], v[154:155]
	v_cvt_pk_bf16_f32 v128, v152, v153
	v_cvt_pk_bf16_f32 v129, v154, v155
	v_add_f32_e32 v132, v138, v139
	v_add_u32_e32 v134, s42, v160
	v_lshlrev_b32_e32 v134, 4, v134
	v_add_u32_e32 v134, s43, v134
	v_subrev_u32_e32 v135, s15, v134
	v_lshrrev_b32_e32 v136, 4, v135
	v_add_u32_e32 v136, v136, v135
	v_mad_u32_u24 v176, v136, s79, v161
	v_lshl_add_u32 v177, v135, 2, s80
	s_and_b32 s2, s43, 3
	s_lshl_b32 s2, s2, s13
	s_lshr_b32 s3, s43, 2
	s_add_i32 s2, s2, s3
	s_lshl_b32 s2, s2, 7
	s_add_u32 s86, s20, s2
	s_addc_u32 s87, s21, 0
	s_add_i32 s2, s42, -64
	v_add_u32_e32 v136, s2, v164
	v_med3_i32 v136, v136, 0, s14
	v_lshl_add_u32 v136, v136, 9, v162
	global_load_dwordx4 v[0:3], v136, s[86:87]
	s_add_i32 s2, s42, -56
	v_add_u32_e32 v135, s2, v164
	v_med3_i32 v135, v135, 0, s14
	v_lshl_add_u32 v135, v135, 9, v162
	global_load_dwordx4 v[4:7], v135, s[86:87]
	s_add_i32 s2, s42, -48
	v_add_u32_e32 v136, s2, v164
	v_med3_i32 v136, v136, 0, s14
	v_lshl_add_u32 v136, v136, 9, v162
	global_load_dwordx4 v[8:11], v136, s[86:87]
	s_add_i32 s2, s42, -40
	v_add_u32_e32 v135, s2, v164
	v_med3_i32 v135, v135, 0, s14
	v_lshl_add_u32 v135, v135, 9, v162
	global_load_dwordx4 v[12:15], v135, s[86:87]
	ds_bpermute_b32 v142, v167, v132
	ds_write_b128 v165, v[64:67]
	ds_write_b128 v165, v[68:71] offset:1152
	ds_write_b128 v165, v[72:75] offset:2304
	ds_write_b128 v165, v[76:79] offset:3456
	s_waitcnt lgkmcnt(0)
	v_add_f32_e32 v132, v132, v142
	ds_bpermute_b32 v142, v168, v132
	ds_read_b64_tr_b16 v[236:237], v166
	ds_read_b64_tr_b16 v[238:239], v166 offset:2304
	ds_read_b64_tr_b16 v[240:241], v166 offset:32
	ds_read_b64_tr_b16 v[242:243], v166 offset:2336
	ds_read_b64_tr_b16 v[244:245], v166 offset:64
	ds_read_b64_tr_b16 v[246:247], v166 offset:2368
	ds_read_b64_tr_b16 v[248:249], v166 offset:96
	ds_read_b64_tr_b16 v[250:251], v166 offset:2400
	s_waitcnt lgkmcnt(0)
	v_add_f32_e32 v132, v132, v142
	ds_write_b128 v165, v[80:83]
	ds_write_b128 v165, v[84:87] offset:1152
	ds_write_b128 v165, v[88:91] offset:2304
	ds_write_b128 v165, v[92:95] offset:3456
	v_mfma_f32_16x16x32_bf16 v[204:207], v[236:239], v[112:115], 0
	v_mfma_f32_16x16x32_bf16 v[208:211], v[240:243], v[112:115], 0
	v_mfma_f32_16x16x32_bf16 v[212:215], v[244:247], v[112:115], 0
	v_mfma_f32_16x16x32_bf16 v[216:219], v[248:251], v[112:115], 0
	s_waitcnt lgkmcnt(0)
	ds_read_b64_tr_b16 v[236:237], v166
	ds_read_b64_tr_b16 v[238:239], v166 offset:2304
	ds_read_b64_tr_b16 v[240:241], v166 offset:32
	ds_read_b64_tr_b16 v[242:243], v166 offset:2336
	ds_read_b64_tr_b16 v[244:245], v166 offset:64
	ds_read_b64_tr_b16 v[246:247], v166 offset:2368
	ds_read_b64_tr_b16 v[248:249], v166 offset:96
	ds_read_b64_tr_b16 v[250:251], v166 offset:2400
	s_waitcnt lgkmcnt(0)
	ds_write_b128 v165, v[96:99]
	ds_write_b128 v165, v[100:103] offset:1152
	ds_write_b128 v165, v[104:107] offset:2304
	ds_write_b128 v165, v[108:111] offset:3456
	v_mfma_f32_16x16x32_bf16 v[204:207], v[236:239], v[116:119], v[204:207]
	v_mfma_f32_16x16x32_bf16 v[208:211], v[240:243], v[116:119], v[208:211]
	v_mfma_f32_16x16x32_bf16 v[212:215], v[244:247], v[116:119], v[212:215]
	v_mfma_f32_16x16x32_bf16 v[216:219], v[248:251], v[116:119], v[216:219]
	s_waitcnt lgkmcnt(0)
	ds_read_b64_tr_b16 v[236:237], v166
	ds_read_b64_tr_b16 v[238:239], v166 offset:2304
	ds_read_b64_tr_b16 v[240:241], v166 offset:32
	ds_read_b64_tr_b16 v[242:243], v166 offset:2336
	ds_read_b64_tr_b16 v[244:245], v166 offset:64
	ds_read_b64_tr_b16 v[246:247], v166 offset:2368
	ds_read_b64_tr_b16 v[248:249], v166 offset:96
	ds_read_b64_tr_b16 v[250:251], v166 offset:2400
	s_waitcnt lgkmcnt(0)
	s_waitcnt vmcnt(6)
	ds_write_b128 v165, v[16:19]
	ds_write_b128 v165, v[20:23] offset:1152
	ds_write_b128 v165, v[24:27] offset:2304
	ds_write_b128 v165, v[28:31] offset:3456
	v_mfma_f32_16x16x32_bf16 v[204:207], v[236:239], v[120:123], v[204:207]
	v_mfma_f32_16x16x32_bf16 v[208:211], v[240:243], v[120:123], v[208:211]
	v_mfma_f32_16x16x32_bf16 v[212:215], v[244:247], v[120:123], v[212:215]
	v_mfma_f32_16x16x32_bf16 v[216:219], v[248:251], v[120:123], v[216:219]
	s_waitcnt lgkmcnt(0)
	ds_read_b64_tr_b16 v[236:237], v166
	ds_read_b64_tr_b16 v[238:239], v166 offset:2304
	ds_read_b64_tr_b16 v[240:241], v166 offset:32
	ds_read_b64_tr_b16 v[242:243], v166 offset:2336
	ds_read_b64_tr_b16 v[244:245], v166 offset:64
	ds_read_b64_tr_b16 v[246:247], v166 offset:2368
	ds_read_b64_tr_b16 v[248:249], v166 offset:96
	ds_read_b64_tr_b16 v[250:251], v166 offset:2400
	s_waitcnt lgkmcnt(0)
	s_add_i32 s2, s42, -32
	v_add_u32_e32 v136, s2, v164
	v_med3_i32 v136, v136, 0, s14
	v_lshl_add_u32 v136, v136, 9, v162
	global_load_dwordx4 v[16:19], v136, s[86:87]
	s_add_i32 s2, s42, -24
	v_add_u32_e32 v135, s2, v164
	v_med3_i32 v135, v135, 0, s14
	v_lshl_add_u32 v135, v135, 9, v162
	global_load_dwordx4 v[20:23], v135, s[86:87]
	s_add_i32 s2, s42, -16
	v_add_u32_e32 v136, s2, v164
	v_med3_i32 v136, v136, 0, s14
	v_lshl_add_u32 v136, v136, 9, v162
	global_load_dwordx4 v[24:27], v136, s[86:87]
	s_add_i32 s2, s42, -8
	v_add_u32_e32 v135, s2, v164
	v_med3_i32 v135, v135, 0, s14
	v_lshl_add_u32 v135, v135, 9, v162
	global_load_dwordx4 v[28:31], v135, s[86:87]
	s_waitcnt vmcnt(8)
	ds_write_b128 v165, v[32:35]
	ds_write_b128 v165, v[36:39] offset:1152
	v_mfma_f32_16x16x32_bf16 v[204:207], v[236:239], v[124:127], v[204:207]
	v_mfma_f32_16x16x32_bf16 v[208:211], v[240:243], v[124:127], v[208:211]
	v_mfma_f32_16x16x32_bf16 v[212:215], v[244:247], v[124:127], v[212:215]
	v_mfma_f32_16x16x32_bf16 v[216:219], v[248:251], v[124:127], v[216:219]
	s_waitcnt lgkmcnt(0)
	ds_read_b64_tr_b16 v[236:237], v166
	ds_read_b64_tr_b16 v[238:239], v166 offset:2304
	ds_read_b64_tr_b16 v[240:241], v166 offset:32
	ds_read_b64_tr_b16 v[242:243], v166 offset:2336
	ds_read_b64_tr_b16 v[244:245], v166 offset:64
	ds_read_b64_tr_b16 v[246:247], v166 offset:2368
	ds_read_b64_tr_b16 v[248:249], v166 offset:96
	ds_read_b64_tr_b16 v[250:251], v166 offset:2400
	s_waitcnt lgkmcnt(0)
	s_add_i32 s2, s42, 0
	v_add_u32_e32 v136, s2, v164
	v_med3_i32 v136, v136, 0, s14
	v_lshl_add_u32 v136, v136, 9, v162
	global_load_dwordx4 v[32:35], v136, s[86:87]
	s_add_i32 s2, s42, 8
	v_add_u32_e32 v135, s2, v164
	v_med3_i32 v135, v135, 0, s14
	v_lshl_add_u32 v135, v135, 9, v162
	global_load_dwordx4 v[36:39], v135, s[86:87]
	s_add_i32 s2, s42, 16
	v_add_u32_e32 v136, s2, v164
	v_med3_i32 v136, v136, 0, s14
	v_lshl_add_u32 v136, v136, 9, v162
	global_load_dwordx4 v[40:43], v136, s[86:87]
	s_add_i32 s2, s42, 24
	v_add_u32_e32 v135, s2, v164
	v_med3_i32 v135, v135, 0, s14
	v_lshl_add_u32 v135, v135, 9, v162
	global_load_dwordx4 v[44:47], v135, s[86:87]
	v_mfma_f32_16x16x32_bf16 v[204:207], v[236:239], v[128:131], v[204:207]
	v_mfma_f32_16x16x32_bf16 v[208:211], v[240:243], v[128:131], v[208:211]
	v_mfma_f32_16x16x32_bf16 v[212:215], v[244:247], v[128:131], v[212:215]
	v_mfma_f32_16x16x32_bf16 v[216:219], v[248:251], v[128:131], v[216:219]
	s_add_i32 s2, s42, 32
	v_add_u32_e32 v136, s2, v164
	v_med3_i32 v136, v136, 0, s14
	v_lshl_add_u32 v136, v136, 9, v162
	global_load_dwordx4 v[120:123], v136, s[86:87]
	s_add_i32 s2, s42, 40
	v_add_u32_e32 v135, s2, v164
	v_med3_i32 v135, v135, 0, s14
	v_lshl_add_u32 v135, v135, 9, v162
	global_load_dwordx4 v[124:127], v135, s[86:87]
	s_add_i32 s2, s42, 48
	v_add_u32_e32 v136, s2, v164
	v_med3_i32 v136, v136, 0, s14
	v_lshl_add_u32 v136, v136, 9, v162
	global_load_dwordx4 v[192:195], v136, s[86:87]
	s_add_i32 s2, s42, 56
	v_add_u32_e32 v135, s2, v164
	v_med3_i32 v135, v135, 0, s14
	v_lshl_add_u32 v135, v135, 9, v162
	global_load_dwordx4 v[196:199], v135, s[86:87]
	s_and_b32 s2, s43, 3
	s_lshl_b32 s2, s2, s13
	s_lshr_b32 s3, s43, 2
	s_add_i32 s2, s2, s3
	s_lshl_b32 s2, s2, 7
	s_add_u32 s74, s22, s2
	s_addc_u32 s75, s23, 0
	s_add_i32 s2, s42, -64
	v_add_u32_e32 v137, s2, v164
	v_med3_i32 v137, v137, 0, s14
	v_lshl_add_u32 v137, v137, 9, v162
	global_load_dwordx4 v[64:67], v137, s[74:75]
	s_add_i32 s2, s42, -56
	v_add_u32_e32 v137, s2, v164
	v_med3_i32 v137, v137, 0, s14
	v_lshl_add_u32 v137, v137, 9, v162
	global_load_dwordx4 v[68:71], v137, s[74:75]
	s_add_i32 s2, s42, -48
	v_add_u32_e32 v137, s2, v164
	v_med3_i32 v137, v137, 0, s14
	v_lshl_add_u32 v137, v137, 9, v162
	global_load_dwordx4 v[72:75], v137, s[74:75]
	s_add_i32 s2, s42, -40
	v_add_u32_e32 v137, s2, v164
	v_med3_i32 v137, v137, 0, s14
	v_lshl_add_u32 v137, v137, 9, v162
	global_load_dwordx4 v[76:79], v137, s[74:75]
	s_and_b32 s2, s43, 3
	s_lshl_b32 s2, s2, s13
	s_lshr_b32 s3, s43, 2
	s_add_i32 s2, s2, s3
	s_lshl_b32 s2, s2, 7
	s_add_u32 s74, s22, s2
	s_addc_u32 s75, s23, 0
	s_add_i32 s2, s42, -32
	v_add_u32_e32 v137, s2, v164
	v_med3_i32 v137, v137, 0, s14
	v_lshl_add_u32 v137, v137, 9, v162
	global_load_dwordx4 v[80:83], v137, s[74:75]
	s_add_i32 s2, s42, -24
	v_add_u32_e32 v137, s2, v164
	v_med3_i32 v137, v137, 0, s14
	v_lshl_add_u32 v137, v137, 9, v162
	global_load_dwordx4 v[84:87], v137, s[74:75]
	s_add_i32 s2, s42, -16
	v_add_u32_e32 v137, s2, v164
	v_med3_i32 v137, v137, 0, s14
	v_lshl_add_u32 v137, v137, 9, v162
	global_load_dwordx4 v[88:91], v137, s[74:75]
	s_add_i32 s2, s42, -8
	v_add_u32_e32 v137, s2, v164
	v_med3_i32 v137, v137, 0, s14
	v_lshl_add_u32 v137, v137, 9, v162
	global_load_dwordx4 v[92:95], v137, s[74:75]
	s_and_b32 s2, s43, 3
	s_lshl_b32 s2, s2, s13
	s_lshr_b32 s3, s43, 2
	s_add_i32 s2, s2, s3
	s_lshl_b32 s2, s2, 7
	s_add_u32 s74, s22, s2
	s_addc_u32 s75, s23, 0
	s_add_i32 s2, s42, 0
	v_add_u32_e32 v137, s2, v164
	v_med3_i32 v137, v137, 0, s14
	v_lshl_add_u32 v137, v137, 9, v162
	global_load_dwordx4 v[96:99], v137, s[74:75]
	s_add_i32 s2, s42, 8
	v_add_u32_e32 v137, s2, v164
	v_med3_i32 v137, v137, 0, s14
	v_lshl_add_u32 v137, v137, 9, v162
	global_load_dwordx4 v[100:103], v137, s[74:75]
	s_add_i32 s2, s42, 16
	v_add_u32_e32 v137, s2, v164
	v_med3_i32 v137, v137, 0, s14
	v_lshl_add_u32 v137, v137, 9, v162
	global_load_dwordx4 v[104:107], v137, s[74:75]
	s_add_i32 s2, s42, 24
	v_add_u32_e32 v137, s2, v164
	v_med3_i32 v137, v137, 0, s14
	v_lshl_add_u32 v137, v137, 9, v162
	global_load_dwordx4 v[108:111], v137, s[74:75]
	ds_read_b128 v[236:239], v173 offset:0
	ds_read_b128 v[240:243], v173 offset:64
	ds_read_b128 v[244:247], v173 offset:128
	ds_read_b128 v[248:251], v173 offset:192
	ds_read_b32 v142, v174 offset:0
	s_waitcnt lgkmcnt(0)
	v_add_f32_e32 v204, v236, v204
	v_add_f32_e32 v205, v237, v205
	v_add_f32_e32 v206, v238, v206
	v_add_f32_e32 v207, v239, v207
	v_add_f32_e32 v208, v240, v208
	v_add_f32_e32 v209, v241, v209
	v_add_f32_e32 v210, v242, v210
	v_add_f32_e32 v211, v243, v211
	v_add_f32_e32 v212, v244, v212
	v_add_f32_e32 v213, v245, v213
	v_add_f32_e32 v214, v246, v214
	v_add_f32_e32 v215, v247, v215
	v_add_f32_e32 v216, v248, v216
	v_add_f32_e32 v217, v249, v217
	v_add_f32_e32 v218, v250, v218
	v_add_f32_e32 v219, v251, v219
	v_add_f32_e32 v132, v142, v132
	ds_write_b128 v173, v[204:207] offset:0
	ds_write_b128 v173, v[208:211] offset:64
	ds_write_b128 v173, v[212:215] offset:128
	ds_write_b128 v173, v[216:219] offset:192
	ds_write_b32 v174, v132 offset:0
	s_mov_b32 s40, s42
	s_mov_b32 s41, s43
	v_mov_b32_e32 v173, v176
	v_mov_b32_e32 v174, v177
	s_lshr_b32 s44, s33, 4
	s_add_i32 s45, s10, s8
	s_cmp_lt_u32 s45, 0x800
	s_cbranch_scc1 .Latt_newunit
	s_mov_b32 s37, 1
	s_branch .Latt_ud_done

.Latt_ud_done:
	s_lshl_b32 s2, s0, 5
	s_add_i32 s42, s15, s2
	s_mov_b32 s43, 0
	v_subrev_u32_e32 v143, s80, v174
	v_lshl_add_u32 v143, v143, 5, v161
	v_add_u32_e32 v143, 0x1b500, v143
	ds_read_b128 v[48:51], v143
	ds_read_b128 v[52:55], v143 offset:64
	s_waitcnt lgkmcnt(0)
	v_mov_b32_e32 v138, 0
	v_mov_b32_e32 v139, 0
	s_waitcnt vmcnt(24)
	ds_write_b128 v165, v[0:3]
	ds_write_b128 v165, v[4:7] offset:1152
	ds_write_b128 v165, v[8:11] offset:2304
	ds_write_b128 v165, v[12:15] offset:3456
	s_waitcnt lgkmcnt(0)
	ds_read_b128 v[204:207], v175
	ds_read_b128 v[208:211], v175 offset:64
	ds_read_b128 v[212:215], v175 offset:2304
	ds_read_b128 v[216:219], v175 offset:2368
	s_and_b32 s2, s41, 3
	s_lshl_b32 s2, s2, s39
	s_lshr_b32 s3, s41, 2
	s_add_i32 s2, s2, s3
	s_lshl_b32 s2, s2, 7
	s_add_u32 s86, s24, s2
	s_addc_u32 s87, s25, 0
	s_add_i32 s2, s40, 64
	v_add_u32_e32 v136, s2, v164
	v_med3_i32 v136, v136, 0, s38
	v_lshl_add_u32 v136, v136, 9, v162
	global_load_dwordx4 v[0:3], v136, s[86:87]
	s_add_i32 s2, s40, 72
	v_add_u32_e32 v135, s2, v164
	v_med3_i32 v135, v135, 0, s38
	v_lshl_add_u32 v135, v135, 9, v162
	global_load_dwordx4 v[4:7], v135, s[86:87]
	s_waitcnt vmcnt(22)
	s_waitcnt lgkmcnt(0)
	ds_write_b128 v165, v[16:19]
	ds_write_b128 v165, v[20:23] offset:1152
	ds_write_b128 v165, v[24:27] offset:2304
	ds_write_b128 v165, v[28:31] offset:3456
	v_mfma_f32_16x16x32_bf16 v[236:239], v[204:207], v[48:51], 0
	v_mfma_f32_16x16x32_bf16 v[236:239], v[208:211], v[52:55], v[236:239]
	v_mfma_f32_16x16x32_bf16 v[240:243], v[212:215], v[48:51], 0
	v_mfma_f32_16x16x32_bf16 v[240:243], v[216:219], v[52:55], v[240:243]
	s_waitcnt lgkmcnt(0)
	ds_read_b128 v[220:223], v175
	ds_read_b128 v[224:227], v175 offset:64
	s_and_b32 s2, s41, 3
	s_lshl_b32 s2, s2, s39
	s_lshr_b32 s3, s41, 2
	s_add_i32 s2, s2, s3
	s_lshl_b32 s2, s2, 7
	s_add_u32 s74, s26, s2
	s_addc_u32 s75, s27, 0
	s_add_i32 s2, s40, 32
	v_add_u32_e32 v137, s2, v164
	v_med3_i32 v137, v137, 0, s38
	v_lshl_add_u32 v137, v137, 9, v162
	global_load_dwordx4 v[16:19], v137, s[74:75]
	s_add_i32 s2, s40, 40
	v_add_u32_e32 v137, s2, v164
	v_med3_i32 v137, v137, 0, s38
	v_lshl_add_u32 v137, v137, 9, v162
	global_load_dwordx4 v[20:23], v137, s[74:75]
	s_add_i32 s2, s40, 48
	v_add_u32_e32 v137, s2, v164
	v_med3_i32 v137, v137, 0, s38
	v_lshl_add_u32 v137, v137, 9, v162
	global_load_dwordx4 v[24:27], v137, s[74:75]
	s_add_i32 s2, s40, 56
	v_add_u32_e32 v137, s2, v164
	v_med3_i32 v137, v137, 0, s38
	v_lshl_add_u32 v137, v137, 9, v162
	global_load_dwordx4 v[28:31], v137, s[74:75]
	s_nop 7
	s_add_i32 s77, s40, -64
	s_cmp_lt_u32 s77, s44
	s_cselect_b32 s76, s70, s71
	v_min_f32_e32 v152, s76, v236
	v_min_f32_e32 v153, s76, v237
	v_min_f32_e32 v154, s76, v238
	v_min_f32_e32 v155, s76, v239
	s_waitcnt lgkmcnt(0)
	v_mfma_f32_16x16x32_bf16 v[236:239], v[220:223], v[48:51], 0
	v_mfma_f32_16x16x32_bf16 v[236:239], v[224:227], v[52:55], v[236:239]
	s_waitcnt vmcnt(24)
	ds_write_b128 v165, v[32:35]
	ds_write_b128 v165, v[36:39] offset:1152
	ds_read_b128 v[228:231], v175 offset:2304
	ds_read_b128 v[232:235], v175 offset:2368
	v_pk_mul_f32 v[152:153], v[152:153], s[72:73]
	v_pk_mul_f32 v[154:155], v[154:155], s[72:73]
	v_exp_f32_e32 v152, v152
	v_exp_f32_e32 v153, v153
	v_exp_f32_e32 v154, v154
	v_exp_f32_e32 v155, v155
	v_cndmask_b32_e64 v152, 0, v152, s[54:55]
	v_cndmask_b32_e64 v153, 0, v153, s[56:57]
	v_cndmask_b32_e64 v154, 0, v154, s[58:59]
	v_cndmask_b32_e64 v155, 0, v155, s[60:61]
	v_pk_add_f32 v[138:139], v[138:139], v[152:153]
	v_pk_add_f32 v[138:139], v[138:139], v[154:155]
	v_cvt_pk_bf16_f32 v112, v152, v153
	v_cvt_pk_bf16_f32 v113, v154, v155
	s_add_i32 s77, s40, -48
	s_cmp_lt_u32 s77, s44
	s_cselect_b32 s76, s70, s71
	v_min_f32_e32 v152, s76, v240
	v_min_f32_e32 v153, s76, v241
	v_min_f32_e32 v154, s76, v242
	v_min_f32_e32 v155, s76, v243
	s_waitcnt lgkmcnt(0)
	v_mfma_f32_16x16x32_bf16 v[240:243], v[228:231], v[48:51], 0
	v_mfma_f32_16x16x32_bf16 v[240:243], v[232:235], v[52:55], v[240:243]
	s_waitcnt vmcnt(22)
	ds_write_b128 v165, v[40:43] offset:2304
	ds_write_b128 v165, v[44:47] offset:3456
	ds_read_b128 v[204:207], v175
	ds_read_b128 v[208:211], v175 offset:64
	v_pk_mul_f32 v[152:153], v[152:153], s[72:73]
	v_pk_mul_f32 v[154:155], v[154:155], s[72:73]
	v_exp_f32_e32 v152, v152
	v_exp_f32_e32 v153, v153
	v_exp_f32_e32 v154, v154
	v_exp_f32_e32 v155, v155
	v_pk_add_f32 v[138:139], v[138:139], v[152:153]
	v_pk_add_f32 v[138:139], v[138:139], v[154:155]
	v_cvt_pk_bf16_f32 v114, v152, v153
	v_cvt_pk_bf16_f32 v115, v154, v155
	s_add_i32 s77, s40, -32
	s_cmp_lt_u32 s77, s44
	s_cselect_b32 s76, s70, s71
	v_min_f32_e32 v152, s76, v236
	v_min_f32_e32 v153, s76, v237
	v_min_f32_e32 v154, s76, v238
	v_min_f32_e32 v155, s76, v239
	s_waitcnt lgkmcnt(0)
	v_mfma_f32_16x16x32_bf16 v[236:239], v[204:207], v[48:51], 0
	v_mfma_f32_16x16x32_bf16 v[236:239], v[208:211], v[52:55], v[236:239]
	s_and_b32 s2, s41, 3
	s_lshl_b32 s2, s2, s39
	s_lshr_b32 s3, s41, 2
	s_add_i32 s2, s2, s3
	s_lshl_b32 s2, s2, 7
	s_add_u32 s74, s26, s2
	s_addc_u32 s75, s27, 0
	s_add_i32 s2, s40, 64
	v_add_u32_e32 v137, s2, v164
	v_med3_i32 v137, v137, 0, s38
	v_lshl_add_u32 v137, v137, 9, v162
	global_load_dwordx4 v[32:35], v137, s[74:75]
	s_add_i32 s2, s40, 72
	v_add_u32_e32 v137, s2, v164
	v_med3_i32 v137, v137, 0, s38
	v_lshl_add_u32 v137, v137, 9, v162
	global_load_dwordx4 v[36:39], v137, s[74:75]
	s_waitcnt vmcnt(22)
	ds_write_b128 v165, v[120:123]
	ds_write_b128 v165, v[124:127] offset:1152
	ds_read_b128 v[212:215], v175 offset:2304
	ds_read_b128 v[216:219], v175 offset:2368
	v_pk_mul_f32 v[152:153], v[152:153], s[72:73]
	v_pk_mul_f32 v[154:155], v[154:155], s[72:73]
	v_exp_f32_e32 v152, v152
	v_exp_f32_e32 v153, v153
	v_exp_f32_e32 v154, v154
	v_exp_f32_e32 v155, v155
	v_pk_add_f32 v[138:139], v[138:139], v[152:153]
	v_pk_add_f32 v[138:139], v[138:139], v[154:155]
	v_cvt_pk_bf16_f32 v116, v152, v153
	v_cvt_pk_bf16_f32 v117, v154, v155
	s_add_i32 s77, s40, -16
	s_cmp_lt_u32 s77, s44
	s_cselect_b32 s76, s70, s71
	v_min_f32_e32 v152, s76, v240
	v_min_f32_e32 v153, s76, v241
	v_min_f32_e32 v154, s76, v242
	v_min_f32_e32 v155, s76, v243
	s_waitcnt lgkmcnt(0)
	v_mfma_f32_16x16x32_bf16 v[240:243], v[212:215], v[48:51], 0
	v_mfma_f32_16x16x32_bf16 v[240:243], v[216:219], v[52:55], v[240:243]
	s_waitcnt vmcnt(20)
	ds_write_b128 v165, v[192:195] offset:2304
	ds_write_b128 v165, v[196:199] offset:3456
	ds_read_b128 v[220:223], v175
	ds_read_b128 v[224:227], v175 offset:64
	v_pk_mul_f32 v[152:153], v[152:153], s[72:73]
	v_pk_mul_f32 v[154:155], v[154:155], s[72:73]
	v_exp_f32_e32 v152, v152
	v_exp_f32_e32 v153, v153
	v_exp_f32_e32 v154, v154
	v_exp_f32_e32 v155, v155
	v_pk_add_f32 v[138:139], v[138:139], v[152:153]
	v_pk_add_f32 v[138:139], v[138:139], v[154:155]
	v_cvt_pk_bf16_f32 v118, v152, v153
	v_cvt_pk_bf16_f32 v119, v154, v155
	s_add_i32 s77, s40, 0
	s_cmp_lt_u32 s77, s44
	s_cselect_b32 s76, s70, s71
	v_min_f32_e32 v152, s76, v236
	v_min_f32_e32 v153, s76, v237
	v_min_f32_e32 v154, s76, v238
	v_min_f32_e32 v155, s76, v239
	s_waitcnt lgkmcnt(0)
	v_mfma_f32_16x16x32_bf16 v[236:239], v[220:223], v[48:51], 0
	v_mfma_f32_16x16x32_bf16 v[236:239], v[224:227], v[52:55], v[236:239]
	s_waitcnt vmcnt(6)
	ds_write_b128 v165, v[0:3]
	ds_write_b128 v165, v[4:7] offset:1152
	ds_read_b128 v[228:231], v175 offset:2304
	ds_read_b128 v[232:235], v175 offset:2368
	v_pk_mul_f32 v[152:153], v[152:153], s[72:73]
	v_pk_mul_f32 v[154:155], v[154:155], s[72:73]
	v_exp_f32_e32 v152, v152
	v_exp_f32_e32 v153, v153
	v_exp_f32_e32 v154, v154
	v_exp_f32_e32 v155, v155
	v_pk_add_f32 v[138:139], v[138:139], v[152:153]
	v_pk_add_f32 v[138:139], v[138:139], v[154:155]
	v_cvt_pk_bf16_f32 v120, v152, v153
	v_cvt_pk_bf16_f32 v121, v154, v155
	s_add_i32 s77, s40, 16
	s_cmp_lt_u32 s77, s44
	s_cselect_b32 s76, s70, s71
	v_min_f32_e32 v152, s76, v240
	v_min_f32_e32 v153, s76, v241
	v_min_f32_e32 v154, s76, v242
	v_min_f32_e32 v155, s76, v243
	s_waitcnt lgkmcnt(0)
	v_mfma_f32_16x16x32_bf16 v[240:243], v[228:231], v[48:51], 0
	v_mfma_f32_16x16x32_bf16 v[240:243], v[232:235], v[52:55], v[240:243]
	ds_read_b128 v[204:207], v175
	ds_read_b128 v[208:211], v175 offset:64
	v_pk_mul_f32 v[152:153], v[152:153], s[72:73]
	v_pk_mul_f32 v[154:155], v[154:155], s[72:73]
	v_exp_f32_e32 v152, v152
	v_exp_f32_e32 v153, v153
	v_exp_f32_e32 v154, v154
	v_exp_f32_e32 v155, v155
	v_pk_add_f32 v[138:139], v[138:139], v[152:153]
	v_pk_add_f32 v[138:139], v[138:139], v[154:155]
	v_cvt_pk_bf16_f32 v122, v152, v153
	v_cvt_pk_bf16_f32 v123, v154, v155
	s_add_i32 s77, s40, 32
	s_cmp_lt_u32 s77, s44
	s_cselect_b32 s76, s70, s71
	v_min_f32_e32 v152, s76, v236
	v_min_f32_e32 v153, s76, v237
	v_min_f32_e32 v154, s76, v238
	v_min_f32_e32 v155, s76, v239
	s_waitcnt lgkmcnt(0)
	v_mfma_f32_16x16x32_bf16 v[236:239], v[204:207], v[48:51], 0
	v_mfma_f32_16x16x32_bf16 v[236:239], v[208:211], v[52:55], v[236:239]
	v_pk_mul_f32 v[152:153], v[152:153], s[72:73]
	v_pk_mul_f32 v[154:155], v[154:155], s[72:73]
	v_exp_f32_e32 v152, v152
	v_exp_f32_e32 v153, v153
	v_exp_f32_e32 v154, v154
	v_exp_f32_e32 v155, v155
	v_pk_add_f32 v[138:139], v[138:139], v[152:153]
	v_pk_add_f32 v[138:139], v[138:139], v[154:155]
	v_cvt_pk_bf16_f32 v124, v152, v153
	v_cvt_pk_bf16_f32 v125, v154, v155
	s_add_i32 s77, s40, 48
	s_cmp_lt_u32 s77, s44
	s_cselect_b32 s76, s70, s71
	v_min_f32_e32 v152, s76, v240
	v_min_f32_e32 v153, s76, v241
	v_min_f32_e32 v154, s76, v242
	v_min_f32_e32 v155, s76, v243
	v_pk_mul_f32 v[152:153], v[152:153], s[72:73]
	v_pk_mul_f32 v[154:155], v[154:155], s[72:73]
	v_exp_f32_e32 v152, v152
	v_exp_f32_e32 v153, v153
	v_exp_f32_e32 v154, v154
	v_exp_f32_e32 v155, v155
	v_pk_add_f32 v[138:139], v[138:139], v[152:153]
	v_pk_add_f32 v[138:139], v[138:139], v[154:155]
	v_cvt_pk_bf16_f32 v126, v152, v153
	v_cvt_pk_bf16_f32 v127, v154, v155
	s_add_i32 s77, s40, 64
	s_cmp_lt_u32 s77, s44
	s_cselect_b32 s76, s70, s71
	v_min_f32_e32 v152, s76, v236
	v_min_f32_e32 v153, s76, v237
	v_min_f32_e32 v154, s76, v238
	v_min_f32_e32 v155, s76, v239
	v_pk_mul_f32 v[152:153], v[152:153], s[72:73]
	v_pk_mul_f32 v[154:155], v[154:155], s[72:73]
	v_exp_f32_e32 v152, v152
	v_exp_f32_e32 v153, v153
	v_exp_f32_e32 v154, v154
	v_exp_f32_e32 v155, v155
	v_cndmask_b32_e64 v152, 0, v152, s[62:63]
	v_cndmask_b32_e64 v153, 0, v153, s[64:65]
	v_cndmask_b32_e64 v154, 0, v154, s[66:67]
	v_cndmask_b32_e64 v155, 0, v155, s[68:69]
	v_pk_add_f32 v[138:139], v[138:139], v[152:153]
	v_pk_add_f32 v[138:139], v[138:139], v[154:155]
	v_cvt_pk_bf16_f32 v128, v152, v153
	v_cvt_pk_bf16_f32 v129, v154, v155
	v_add_f32_e32 v132, v138, v139
	v_add_u32_e32 v134, s42, v160
	v_add_u32_e32 v134, s43, v134
	v_subrev_u32_e32 v135, s15, v134
	v_lshrrev_b32_e32 v136, 4, v135
	v_add_u32_e32 v136, v136, v135
	v_mad_u32_u24 v176, v136, s79, v161
	v_lshl_add_u32 v177, v135, 2, s80
	s_mul_i32 s2, s0, 48
	s_add_i32 s2, s2, s15
	s_add_i32 s2, s2, -64
	v_add_u32_e32 v138, s2, v164
	v_and_b32_e32 v139, 3, v138
	v_lshlrev_b32_e32 v139, s13, v139
	v_bfe_u32 v140, v138, 2, 2
	v_add_u32_e32 v139, v139, v140
	v_lshl_add_u32 v139, v139, 7, v162
	v_ashrrev_i32_e32 v138, 4, v138
	v_med3_i32 v138, v138, 0, s14
	v_lshl_add_u32 v138, v138, 9, v139
	global_load_dwordx4 v[0:3], v138, s[20:21]
	s_mul_i32 s2, s0, 48
	s_add_i32 s2, s2, s15
	s_add_i32 s2, s2, -56
	v_add_u32_e32 v138, s2, v164
	v_and_b32_e32 v139, 3, v138
	v_lshlrev_b32_e32 v139, s13, v139
	v_bfe_u32 v140, v138, 2, 2
	v_add_u32_e32 v139, v139, v140
	v_lshl_add_u32 v139, v139, 7, v162
	v_ashrrev_i32_e32 v138, 4, v138
	v_med3_i32 v138, v138, 0, s14
	v_lshl_add_u32 v138, v138, 9, v139
	global_load_dwordx4 v[4:7], v138, s[20:21]
	s_mul_i32 s2, s0, 48
	s_add_i32 s2, s2, s15
	s_add_i32 s2, s2, -48
	v_add_u32_e32 v138, s2, v164
	v_and_b32_e32 v139, 3, v138
	v_lshlrev_b32_e32 v139, s13, v139
	v_bfe_u32 v140, v138, 2, 2
	v_add_u32_e32 v139, v139, v140
	v_lshl_add_u32 v139, v139, 7, v162
	v_ashrrev_i32_e32 v138, 4, v138
	v_med3_i32 v138, v138, 0, s14
	v_lshl_add_u32 v138, v138, 9, v139
	global_load_dwordx4 v[8:11], v138, s[20:21]
	s_mul_i32 s2, s0, 48
	s_add_i32 s2, s2, s15
	s_add_i32 s2, s2, -40
	v_add_u32_e32 v138, s2, v164
	v_and_b32_e32 v139, 3, v138
	v_lshlrev_b32_e32 v139, s13, v139
	v_bfe_u32 v140, v138, 2, 2
	v_add_u32_e32 v139, v139, v140
	v_lshl_add_u32 v139, v139, 7, v162
	v_ashrrev_i32_e32 v138, 4, v138
	v_med3_i32 v138, v138, 0, s14
	v_lshl_add_u32 v138, v138, 9, v139
	global_load_dwordx4 v[12:15], v138, s[20:21]
	s_lshl_b32 s2, s0, 5
	s_add_i32 s2, s2, s15
	s_add_i32 s2, s2, 0
	v_add_u32_e32 v138, s2, v164
	v_and_b32_e32 v139, 3, v138
	v_lshlrev_b32_e32 v139, s13, v139
	v_lshrrev_b32_e32 v140, 2, v138
	v_add_u32_e32 v139, v139, v140
	v_lshl_add_u32 v139, v139, 7, v162
	global_load_dwordx4 v[48:51], v139, s[18:19]
	s_lshl_b32 s2, s0, 5
	s_add_i32 s2, s2, s15
	s_add_i32 s2, s2, 8
	v_add_u32_e32 v138, s2, v164
	v_and_b32_e32 v139, 3, v138
	v_lshlrev_b32_e32 v139, s13, v139
	v_lshrrev_b32_e32 v140, 2, v138
	v_add_u32_e32 v139, v139, v140
	v_lshl_add_u32 v139, v139, 7, v162
	global_load_dwordx4 v[52:55], v139, s[18:19]
	s_lshl_b32 s2, s0, 5
	s_add_i32 s2, s2, s15
	s_add_i32 s2, s2, 16
	v_add_u32_e32 v138, s2, v164
	v_and_b32_e32 v139, 3, v138
	v_lshlrev_b32_e32 v139, s13, v139
	v_lshrrev_b32_e32 v140, 2, v138
	v_add_u32_e32 v139, v139, v140
	v_lshl_add_u32 v139, v139, 7, v162
	global_load_dwordx4 v[56:59], v139, s[18:19]
	s_lshl_b32 s2, s0, 5
	s_add_i32 s2, s2, s15
	s_add_i32 s2, s2, 24
	v_add_u32_e32 v138, s2, v164
	v_and_b32_e32 v139, 3, v138
	v_lshlrev_b32_e32 v139, s13, v139
	v_lshrrev_b32_e32 v140, 2, v138
	v_add_u32_e32 v139, v139, v140
	v_lshl_add_u32 v139, v139, 7, v162
	global_load_dwordx4 v[60:63], v139, s[18:19]
	ds_bpermute_b32 v142, v167, v132
	ds_write_b128 v165, v[64:67]
	ds_write_b128 v165, v[68:71] offset:1152
	ds_write_b128 v165, v[72:75] offset:2304
	ds_write_b128 v165, v[76:79] offset:3456
	s_waitcnt lgkmcnt(0)
	v_add_f32_e32 v132, v132, v142
	ds_bpermute_b32 v142, v168, v132
	ds_read_b64_tr_b16 v[236:237], v166
	ds_read_b64_tr_b16 v[238:239], v166 offset:2304
	ds_read_b64_tr_b16 v[240:241], v166 offset:32
	ds_read_b64_tr_b16 v[242:243], v166 offset:2336
	ds_read_b64_tr_b16 v[244:245], v166 offset:64
	ds_read_b64_tr_b16 v[246:247], v166 offset:2368
	ds_read_b64_tr_b16 v[248:249], v166 offset:96
	ds_read_b64_tr_b16 v[250:251], v166 offset:2400
	s_waitcnt lgkmcnt(0)
	v_add_f32_e32 v132, v132, v142
	ds_write_b128 v165, v[80:83]
	ds_write_b128 v165, v[84:87] offset:1152
	ds_write_b128 v165, v[88:91] offset:2304
	ds_write_b128 v165, v[92:95] offset:3456
	v_mfma_f32_16x16x32_bf16 v[204:207], v[236:239], v[112:115], 0
	v_mfma_f32_16x16x32_bf16 v[208:211], v[240:243], v[112:115], 0
	v_mfma_f32_16x16x32_bf16 v[212:215], v[244:247], v[112:115], 0
	v_mfma_f32_16x16x32_bf16 v[216:219], v[248:251], v[112:115], 0
	s_waitcnt lgkmcnt(0)
	ds_read_b64_tr_b16 v[236:237], v166
	ds_read_b64_tr_b16 v[238:239], v166 offset:2304
	ds_read_b64_tr_b16 v[240:241], v166 offset:32
	ds_read_b64_tr_b16 v[242:243], v166 offset:2336
	ds_read_b64_tr_b16 v[244:245], v166 offset:64
	ds_read_b64_tr_b16 v[246:247], v166 offset:2368
	ds_read_b64_tr_b16 v[248:249], v166 offset:96
	ds_read_b64_tr_b16 v[250:251], v166 offset:2400
	s_waitcnt lgkmcnt(0)
	ds_write_b128 v165, v[96:99]
	ds_write_b128 v165, v[100:103] offset:1152
	ds_write_b128 v165, v[104:107] offset:2304
	ds_write_b128 v165, v[108:111] offset:3456
	v_mfma_f32_16x16x32_bf16 v[204:207], v[236:239], v[116:119], v[204:207]
	v_mfma_f32_16x16x32_bf16 v[208:211], v[240:243], v[116:119], v[208:211]
	v_mfma_f32_16x16x32_bf16 v[212:215], v[244:247], v[116:119], v[212:215]
	v_mfma_f32_16x16x32_bf16 v[216:219], v[248:251], v[116:119], v[216:219]
	s_waitcnt lgkmcnt(0)
	ds_read_b64_tr_b16 v[236:237], v166
	ds_read_b64_tr_b16 v[238:239], v166 offset:2304
	ds_read_b64_tr_b16 v[240:241], v166 offset:32
	ds_read_b64_tr_b16 v[242:243], v166 offset:2336
	ds_read_b64_tr_b16 v[244:245], v166 offset:64
	ds_read_b64_tr_b16 v[246:247], v166 offset:2368
	ds_read_b64_tr_b16 v[248:249], v166 offset:96
	ds_read_b64_tr_b16 v[250:251], v166 offset:2400
	s_waitcnt lgkmcnt(0)
	s_waitcnt vmcnt(10)
	ds_write_b128 v165, v[16:19]
	ds_write_b128 v165, v[20:23] offset:1152
	ds_write_b128 v165, v[24:27] offset:2304
	ds_write_b128 v165, v[28:31] offset:3456
	v_mfma_f32_16x16x32_bf16 v[204:207], v[236:239], v[120:123], v[204:207]
	v_mfma_f32_16x16x32_bf16 v[208:211], v[240:243], v[120:123], v[208:211]
	v_mfma_f32_16x16x32_bf16 v[212:215], v[244:247], v[120:123], v[212:215]
	v_mfma_f32_16x16x32_bf16 v[216:219], v[248:251], v[120:123], v[216:219]
	s_waitcnt lgkmcnt(0)
	ds_read_b64_tr_b16 v[236:237], v166
	ds_read_b64_tr_b16 v[238:239], v166 offset:2304
	ds_read_b64_tr_b16 v[240:241], v166 offset:32
	ds_read_b64_tr_b16 v[242:243], v166 offset:2336
	ds_read_b64_tr_b16 v[244:245], v166 offset:64
	ds_read_b64_tr_b16 v[246:247], v166 offset:2368
	ds_read_b64_tr_b16 v[248:249], v166 offset:96
	ds_read_b64_tr_b16 v[250:251], v166 offset:2400
	s_waitcnt lgkmcnt(0)
	s_mul_i32 s2, s0, 48
	s_add_i32 s2, s2, s15
	s_add_i32 s2, s2, -32
	v_add_u32_e32 v138, s2, v164
	v_and_b32_e32 v139, 3, v138
	v_lshlrev_b32_e32 v139, s13, v139
	v_bfe_u32 v140, v138, 2, 2
	v_add_u32_e32 v139, v139, v140
	v_lshl_add_u32 v139, v139, 7, v162
	v_ashrrev_i32_e32 v138, 4, v138
	v_med3_i32 v138, v138, 0, s14
	v_lshl_add_u32 v138, v138, 9, v139
	global_load_dwordx4 v[16:19], v138, s[20:21]
	s_mul_i32 s2, s0, 48
	s_add_i32 s2, s2, s15
	s_add_i32 s2, s2, -24
	v_add_u32_e32 v138, s2, v164
	v_and_b32_e32 v139, 3, v138
	v_lshlrev_b32_e32 v139, s13, v139
	v_bfe_u32 v140, v138, 2, 2
	v_add_u32_e32 v139, v139, v140
	v_lshl_add_u32 v139, v139, 7, v162
	v_ashrrev_i32_e32 v138, 4, v138
	v_med3_i32 v138, v138, 0, s14
	v_lshl_add_u32 v138, v138, 9, v139
	global_load_dwordx4 v[20:23], v138, s[20:21]
	s_mul_i32 s2, s0, 48
	s_add_i32 s2, s2, s15
	s_add_i32 s2, s2, -64
	v_add_u32_e32 v138, s2, v164
	v_and_b32_e32 v139, 3, v138
	v_lshlrev_b32_e32 v139, s13, v139
	v_bfe_u32 v140, v138, 2, 2
	v_add_u32_e32 v139, v139, v140
	v_lshl_add_u32 v139, v139, 7, v162
	v_ashrrev_i32_e32 v138, 4, v138
	v_med3_i32 v138, v138, 0, s14
	v_lshl_add_u32 v138, v138, 9, v139
	global_load_dwordx4 v[24:27], v138, s[22:23]
	s_mul_i32 s2, s0, 48
	s_add_i32 s2, s2, s15
	s_add_i32 s2, s2, -56
	v_add_u32_e32 v138, s2, v164
	v_and_b32_e32 v139, 3, v138
	v_lshlrev_b32_e32 v139, s13, v139
	v_bfe_u32 v140, v138, 2, 2
	v_add_u32_e32 v139, v139, v140
	v_lshl_add_u32 v139, v139, 7, v162
	v_ashrrev_i32_e32 v138, 4, v138
	v_med3_i32 v138, v138, 0, s14
	v_lshl_add_u32 v138, v138, 9, v139
	global_load_dwordx4 v[28:31], v138, s[22:23]
	s_waitcnt vmcnt(12)
	ds_write_b128 v165, v[32:35]
	ds_write_b128 v165, v[36:39] offset:1152
	v_mfma_f32_16x16x32_bf16 v[204:207], v[236:239], v[124:127], v[204:207]
	v_mfma_f32_16x16x32_bf16 v[208:211], v[240:243], v[124:127], v[208:211]
	v_mfma_f32_16x16x32_bf16 v[212:215], v[244:247], v[124:127], v[212:215]
	v_mfma_f32_16x16x32_bf16 v[216:219], v[248:251], v[124:127], v[216:219]
	s_waitcnt lgkmcnt(0)
	ds_read_b64_tr_b16 v[236:237], v166
	ds_read_b64_tr_b16 v[238:239], v166 offset:2304
	ds_read_b64_tr_b16 v[240:241], v166 offset:32
	ds_read_b64_tr_b16 v[242:243], v166 offset:2336
	ds_read_b64_tr_b16 v[244:245], v166 offset:64
	ds_read_b64_tr_b16 v[246:247], v166 offset:2368
	ds_read_b64_tr_b16 v[248:249], v166 offset:96
	ds_read_b64_tr_b16 v[250:251], v166 offset:2400
	s_waitcnt lgkmcnt(0)
	s_mul_i32 s2, s0, 48
	s_add_i32 s2, s2, s15
	s_add_i32 s2, s2, -48
	v_add_u32_e32 v138, s2, v164
	v_and_b32_e32 v139, 3, v138
	v_lshlrev_b32_e32 v139, s13, v139
	v_bfe_u32 v140, v138, 2, 2
	v_add_u32_e32 v139, v139, v140
	v_lshl_add_u32 v139, v139, 7, v162
	v_ashrrev_i32_e32 v138, 4, v138
	v_med3_i32 v138, v138, 0, s14
	v_lshl_add_u32 v138, v138, 9, v139
	global_load_dwordx4 v[32:35], v138, s[22:23]
	s_mul_i32 s2, s0, 48
	s_add_i32 s2, s2, s15
	s_add_i32 s2, s2, -40
	v_add_u32_e32 v138, s2, v164
	v_and_b32_e32 v139, 3, v138
	v_lshlrev_b32_e32 v139, s13, v139
	v_bfe_u32 v140, v138, 2, 2
	v_add_u32_e32 v139, v139, v140
	v_lshl_add_u32 v139, v139, 7, v162
	v_ashrrev_i32_e32 v138, 4, v138
	v_med3_i32 v138, v138, 0, s14
	v_lshl_add_u32 v138, v138, 9, v139
	global_load_dwordx4 v[36:39], v138, s[22:23]
	s_mul_i32 s2, s0, 48
	s_add_i32 s2, s2, s15
	s_add_i32 s2, s2, -32
	v_add_u32_e32 v138, s2, v164
	v_and_b32_e32 v139, 3, v138
	v_lshlrev_b32_e32 v139, s13, v139
	v_bfe_u32 v140, v138, 2, 2
	v_add_u32_e32 v139, v139, v140
	v_lshl_add_u32 v139, v139, 7, v162
	v_ashrrev_i32_e32 v138, 4, v138
	v_med3_i32 v138, v138, 0, s14
	v_lshl_add_u32 v138, v138, 9, v139
	global_load_dwordx4 v[40:43], v138, s[22:23]
	s_mul_i32 s2, s0, 48
	s_add_i32 s2, s2, s15
	s_add_i32 s2, s2, -24
	v_add_u32_e32 v138, s2, v164
	v_and_b32_e32 v139, 3, v138
	v_lshlrev_b32_e32 v139, s13, v139
	v_bfe_u32 v140, v138, 2, 2
	v_add_u32_e32 v139, v139, v140
	v_lshl_add_u32 v139, v139, 7, v162
	v_ashrrev_i32_e32 v138, 4, v138
	v_med3_i32 v138, v138, 0, s14
	v_lshl_add_u32 v138, v138, 9, v139
	global_load_dwordx4 v[44:47], v138, s[22:23]
	v_mfma_f32_16x16x32_bf16 v[204:207], v[236:239], v[128:131], v[204:207]
	v_mfma_f32_16x16x32_bf16 v[208:211], v[240:243], v[128:131], v[208:211]
	v_mfma_f32_16x16x32_bf16 v[212:215], v[244:247], v[128:131], v[212:215]
	v_mfma_f32_16x16x32_bf16 v[216:219], v[248:251], v[128:131], v[216:219]
	ds_read_b128 v[236:239], v173 offset:0
	ds_read_b128 v[240:243], v173 offset:64
	ds_read_b128 v[244:247], v173 offset:128
	ds_read_b128 v[248:251], v173 offset:192
	ds_read_b32 v142, v174 offset:0
	s_waitcnt lgkmcnt(0)
	v_add_f32_e32 v204, v236, v204
	v_add_f32_e32 v205, v237, v205
	v_add_f32_e32 v206, v238, v206
	v_add_f32_e32 v207, v239, v207
	v_add_f32_e32 v208, v240, v208
	v_add_f32_e32 v209, v241, v209
	v_add_f32_e32 v210, v242, v210
	v_add_f32_e32 v211, v243, v211
	v_add_f32_e32 v212, v244, v212
	v_add_f32_e32 v213, v245, v213
	v_add_f32_e32 v214, v246, v214
	v_add_f32_e32 v215, v247, v215
	v_add_f32_e32 v216, v248, v216
	v_add_f32_e32 v217, v249, v217
	v_add_f32_e32 v218, v250, v218
	v_add_f32_e32 v219, v251, v219
	v_add_f32_e32 v132, v142, v132
	ds_write_b128 v173, v[204:207] offset:0
	ds_write_b128 v173, v[208:211] offset:64
	ds_write_b128 v173, v[212:215] offset:128
	ds_write_b128 v173, v[216:219] offset:192
	ds_write_b32 v174, v132 offset:0
	s_waitcnt lgkmcnt(0)
	s_barrier
	ds_read_b128 v[204:207], v170
	ds_read_b128 v[208:211], v170 offset:16
	ds_read_b128 v[212:215], v170 offset:32
	ds_read_b128 v[216:219], v170 offset:48
	ds_read_b128 v[220:223], v170 offset:64
	ds_read_b128 v[224:227], v170 offset:80
	ds_read_b128 v[228:231], v170 offset:96
	ds_read_b128 v[232:235], v170 offset:112
	ds_read_b32 v142, v171
	s_lshl_b32 s2, s35, 11
	s_lshl_b32 s3, s36, 7
	s_add_u32 s2, s2, s3
	s_add_u32 s90, s6, s2
	s_addc_u32 s91, s7, 0
	s_waitcnt lgkmcnt(0)
	v_div_scale_f32 v143, s[30:31], v142, v142, 1.0
	v_rcp_f32_e32 v147, v143
	v_div_scale_f32 v134, vcc, 1.0, v142, 1.0
	v_fma_f32 v135, -v143, v147, 1.0
	v_fmac_f32_e32 v147, v135, v147
	v_mul_f32_e32 v135, v134, v147
	v_fma_f32 v136, -v143, v135, v134
	v_fmac_f32_e32 v135, v136, v147
	v_fma_f32 v143, -v143, v135, v134
	v_div_fmas_f32 v143, v143, v147, v135
	v_div_fixup_f32 v142, v143, v142, 1.0
	v_mul_f32_e32 v204, v142, v204
	v_mul_f32_e32 v205, v142, v205
	v_mul_f32_e32 v206, v142, v206
	v_mul_f32_e32 v207, v142, v207
	v_mul_f32_e32 v208, v142, v208
	v_mul_f32_e32 v209, v142, v209
	v_mul_f32_e32 v210, v142, v210
	v_mul_f32_e32 v211, v142, v211
	v_mul_f32_e32 v212, v142, v212
	v_mul_f32_e32 v213, v142, v213
	v_mul_f32_e32 v214, v142, v214
	v_mul_f32_e32 v215, v142, v215
	v_mul_f32_e32 v216, v142, v216
	v_mul_f32_e32 v217, v142, v217
	v_mul_f32_e32 v218, v142, v218
	v_mul_f32_e32 v219, v142, v219
	v_mul_f32_e32 v220, v142, v220
	v_mul_f32_e32 v221, v142, v221
	v_mul_f32_e32 v222, v142, v222
	v_mul_f32_e32 v223, v142, v223
	v_mul_f32_e32 v224, v142, v224
	v_mul_f32_e32 v225, v142, v225
	v_mul_f32_e32 v226, v142, v226
	v_mul_f32_e32 v227, v142, v227
	v_mul_f32_e32 v228, v142, v228
	v_mul_f32_e32 v229, v142, v229
	v_mul_f32_e32 v230, v142, v230
	v_mul_f32_e32 v231, v142, v231
	v_mul_f32_e32 v232, v142, v232
	v_mul_f32_e32 v233, v142, v233
	v_mul_f32_e32 v234, v142, v234
	v_mul_f32_e32 v235, v142, v235
	v_cvt_pk_bf16_f32 v112, v204, v205
	v_cvt_pk_bf16_f32 v113, v206, v207
	v_cvt_pk_bf16_f32 v114, v208, v209
	v_cvt_pk_bf16_f32 v115, v210, v211
	v_cvt_pk_bf16_f32 v116, v212, v213
	v_cvt_pk_bf16_f32 v117, v214, v215
	v_cvt_pk_bf16_f32 v118, v216, v217
	v_cvt_pk_bf16_f32 v119, v218, v219
	v_cvt_pk_bf16_f32 v120, v220, v221
	v_cvt_pk_bf16_f32 v121, v222, v223
	v_cvt_pk_bf16_f32 v122, v224, v225
	v_cvt_pk_bf16_f32 v123, v226, v227
	v_cvt_pk_bf16_f32 v124, v228, v229
	v_cvt_pk_bf16_f32 v125, v230, v231
	v_cvt_pk_bf16_f32 v126, v232, v233
	v_cvt_pk_bf16_f32 v127, v234, v235
	global_store_dwordx4 v172, v[112:115], s[90:91] nt
	global_store_dwordx4 v172, v[116:119], s[90:91] offset:16 nt
	global_store_dwordx4 v172, v[120:123], s[90:91] offset:32 nt
	global_store_dwordx4 v172, v[124:127], s[90:91] offset:48 nt
	s_barrier
	s_cmp_eq_u32 s37, 0
	s_cbranch_scc1 .Latt_unit
	s_waitcnt vmcnt(0)
	s_branch .LBB0_365
